# r4a with the phase-0 GEMV in rolling-prefetch form (next trip's row i issued when row i is consumed), no loop-exit drain
# speedup vs baseline: 1.0027x; 1.0027x over previous
; #define LAS __attribute__((address_space(3)))
; __device__ __forceinline__ void phase0(CArgs a, LAS unsigned char* lds, int tid, int lane, int wave, int G, int bx) {
;     ...
;             for (int kk = 0; kk < 128; kk += 16) {
;                 const int k = kb + kk; const float* wp = Wl + (size_t)(half * 1024 + k) * NMOD;
;                 f32x2 wv[16];
; #pragma unroll
;                 for (int i = 0; i < 16; ++i) wv[i] = __builtin_nontemporal_load((const f32x2*)(wp + (size_t)i * NMOD));
; #pragma unroll
;                 for (int q = 0; q < 4; ++q) {
; #pragma unroll
;                     for (int r = 0; r < NB; ++r) { const f32x4 s4 = *(const LAS f32x4*)(S + r * 1024 + k + 4 * q);
;                         acc[r] += wv[4 * q] * s4[0]; acc[r] += wv[4 * q + 1] * s4[1]; acc[r] += wv[4 * q + 2] * s4[2]; acc[r] += wv[4 * q + 3] * s4[3]; } }
.LBB0_843:
	s_cmp_eq_u32 s2, 0x60
	s_cselect_b32 s48, 0, 0xc0000
	s_mov_b32 s49, 0
	v_lshl_add_u64 v[208:209], v[12:13], 0, s[48:49]
	s_mov_b32 s6, 0xfff4c000
	v_add_co_u32_e32 v34, vcc, s6, v12
	s_mov_b32 s6, 0xfff58000
	s_nop 0
	v_addc_co_u32_e32 v35, vcc, -1, v13, vcc
	v_add_co_u32_e32 v42, vcc, s6, v12
	s_mov_b32 s6, 0xfff64000
	s_nop 0
	v_addc_co_u32_e32 v43, vcc, -1, v13, vcc
	v_add_co_u32_e32 v44, vcc, s6, v12
	s_mov_b32 s6, 0xfff70000
	s_nop 0
	v_addc_co_u32_e32 v45, vcc, -1, v13, vcc
	v_add_co_u32_e32 v46, vcc, s6, v12
	s_add_i32 s6, s3, 0xfffdefd0
	s_nop 0
	v_addc_co_u32_e32 v47, vcc, -1, v13, vcc
	s_nop 0
	s_add_i32 s7, s3, 0xfffdffd0
	s_add_i32 s8, s3, 0xfffe0fd0
	s_add_i32 s9, s3, 0xfffe1fd0
	s_add_i32 s14, s3, 0xfffe2fd0
	s_add_i32 s15, s3, 0xfffe3fd0
	s_add_i32 s16, s3, 0xfffe4fd0
	s_add_i32 s17, s3, 0xfffe5fd0
	v_mov_b32_e32 v42, s6
	v_mov_b32_e32 v46, s7
	v_mov_b32_e32 v50, s8
	v_mov_b32_e32 v54, s9
	v_mov_b32_e32 v58, s14
	v_mov_b32_e32 v62, s15
	v_mov_b32_e32 v66, s16
	v_mov_b32_e32 v70, s17
	ds_read_b128 v[42:45], v42
	ds_read_b128 v[46:49], v46
	ds_read_b128 v[50:53], v50
	ds_read_b128 v[54:57], v54
	ds_read_b128 v[58:61], v58
	ds_read_b128 v[62:65], v62
	ds_read_b128 v[66:69], v66
	ds_read_b128 v[70:73], v70
	s_add_i32 s18, s3, 0xfffe6fd0
	v_mov_b32_e32 v97, s18
	s_add_i32 s19, s3, 0xfffe7fd0
	s_waitcnt lgkmcnt(7)
	v_mov_b32_e32 v98, v45
	v_mov_b32_e32 v99, s19
	s_add_i32 s20, s3, 0xfffe8fd0
	s_waitcnt lgkmcnt(6)
	v_mov_b32_e32 v96, v49
	v_mov_b32_e32 v103, s20
	s_add_i32 s21, s3, 0xfffe9fd0
	s_waitcnt lgkmcnt(5)
	v_mov_b32_e32 v102, v53
	v_mov_b32_e32 v104, s21
	s_add_i32 s22, s3, 0xfffeafd0
	s_waitcnt lgkmcnt(4)
	v_mov_b32_e32 v112, v57
	s_add_i32 s23, s3, 0xfffebfd0
	v_mov_b32_e32 v105, s22
	v_mov_b32_e32 v106, s23
	s_waitcnt lgkmcnt(3)
	v_mov_b32_e32 v110, v61
	s_waitcnt lgkmcnt(2)
	v_mov_b32_e32 v118, v65
	s_add_i32 s24, s3, 0xfffecfd0
	v_mov_b32_e32 v107, s24
	s_add_i32 s25, s3, 0xfffedfd0
	s_add_i32 s26, s3, 0xfffeefd0
	s_add_i32 s27, s3, 0xfffeffd0
	v_mov_b32_e32 v111, s25
	v_mov_b32_e32 v113, s26
	v_mov_b32_e32 v119, s27
	s_waitcnt lgkmcnt(1)
	v_mov_b32_e32 v124, v69
	s_waitcnt lgkmcnt(0)
	v_mov_b32_e32 v122, v73
	s_add_i32 s28, s3, 0xffff0fd0
	s_add_i32 s29, s3, 0xffff1fd0
	v_mov_b32_e32 v123, s28
	v_mov_b32_e32 v125, s29
	s_add_i32 s30, s3, 0xffff2fd0
	s_add_i32 s31, s3, 0xffff3fd0
	v_mov_b32_e32 v131, s30
	v_mov_b32_e32 v154, s31
	s_add_i32 s6, s3, 0xffff4fd0
	s_add_i32 s7, s3, 0xffff5fd0
	s_add_i32 s8, s3, 0xfffe0fe0
	s_add_i32 s9, s3, 0xfffe1fe0
	s_add_i32 s31, s3, 0xffff3fe0
	s_add_i32 s14, s3, 0xfffe2fe0
	s_add_i32 s15, s3, 0xfffe3fe0
	s_add_i32 s16, s3, 0xfffe4fe0
	s_add_i32 s17, s3, 0xfffe5fe0
	s_add_i32 s18, s3, 0xfffe6fe0
	s_add_i32 s19, s3, 0xfffe7fe0
	s_add_i32 s20, s3, 0xfffe8fe0
	s_add_i32 s21, s3, 0xfffe9fe0
	s_add_i32 s22, s3, 0xfffeafe0
	s_add_i32 s23, s3, 0xfffebfe0
	s_add_i32 s24, s3, 0xfffecfe0
	s_add_i32 s25, s3, 0xfffedfe0
	s_add_i32 s26, s3, 0xfffeefe0
	s_add_i32 s27, s3, 0xfffeffe0
	s_add_i32 s28, s3, 0xffff0fe0
	s_add_i32 s29, s3, 0xffff1fe0
	s_add_i32 s30, s3, 0xffff2fe0
	s_add_i32 s33, s3, 0xffff5000
	s_add_i32 s34, s3, 0xffff6000
	s_waitcnt vmcnt(15)
	v_mov_b32_e32 v90, v220
	v_mov_b32_e32 v91, v221
	s_mov_b32 s44, 0xfff4c000
	v_lshl_add_u64 v[206:207], v[208:209], 0, s[44:45]
	global_load_dwordx2 v[220:221], v[206:207], off nt
	v_pk_fma_f32 v[88:89], v[90:91], v[42:43], v[88:89] op_sel_hi:[1,0,1]
	s_add_i32 s2, s2, 16
	s_waitcnt vmcnt(15)
	v_mov_b32_e32 v92, v222
	v_mov_b32_e32 v93, v223
	s_mov_b32 s44, 0xfff58000
	v_lshl_add_u64 v[206:207], v[208:209], 0, s[44:45]
	global_load_dwordx2 v[222:223], v[206:207], off nt
	v_pk_fma_f32 v[42:43], v[92:93], v[42:43], v[88:89] op_sel:[0,1,0]
	s_waitcnt vmcnt(15)
	v_mov_b32_e32 v94, v224
	v_mov_b32_e32 v95, v225
	s_mov_b32 s44, 0xfff64000
	v_lshl_add_u64 v[206:207], v[208:209], 0, s[44:45]
	global_load_dwordx2 v[224:225], v[206:207], off nt
	v_pk_fma_f32 v[88:89], v[94:95], v[44:45], v[42:43] op_sel_hi:[1,0,1]
	v_pk_fma_f32 v[42:43], v[90:91], v[46:47], v[86:87] op_sel_hi:[1,0,1]
	s_waitcnt vmcnt(15)
	v_mov_b32_e32 v34, v226
	v_mov_b32_e32 v35, v227
	s_mov_b32 s44, 0xfff70000
	v_lshl_add_u64 v[206:207], v[208:209], 0, s[44:45]
	global_load_dwordx2 v[226:227], v[206:207], off nt
	v_pk_fma_f32 v[156:157], v[34:35], v[98:99], v[88:89] op_sel_hi:[1,0,1]
	v_pk_fma_f32 v[42:43], v[92:93], v[46:47], v[42:43] op_sel:[0,1,0]
	v_pk_fma_f32 v[46:47], v[90:91], v[50:51], v[84:85] op_sel_hi:[1,0,1]
	v_pk_fma_f32 v[86:87], v[94:95], v[48:49], v[42:43] op_sel_hi:[1,0,1]
	ds_read_b128 v[42:45], v97
	v_pk_fma_f32 v[46:47], v[92:93], v[50:51], v[46:47] op_sel:[0,1,0]
	v_pk_fma_f32 v[50:51], v[90:91], v[54:55], v[82:83] op_sel_hi:[1,0,1]
	v_pk_fma_f32 v[100:101], v[94:95], v[52:53], v[46:47] op_sel_hi:[1,0,1]
	v_pk_fma_f32 v[50:51], v[92:93], v[54:55], v[50:51] op_sel:[0,1,0]
	ds_read_b128 v[46:49], v99
	v_pk_fma_f32 v[108:109], v[94:95], v[56:57], v[50:51] op_sel_hi:[1,0,1]
	v_pk_fma_f32 v[50:51], v[90:91], v[58:59], v[80:81] op_sel_hi:[1,0,1]
	v_pk_fma_f32 v[54:55], v[90:91], v[62:63], v[78:79] op_sel_hi:[1,0,1]
	v_pk_fma_f32 v[50:51], v[92:93], v[58:59], v[50:51] op_sel:[0,1,0]
	v_pk_fma_f32 v[58:59], v[90:91], v[66:67], v[76:77] op_sel_hi:[1,0,1]
	v_pk_fma_f32 v[114:115], v[94:95], v[60:61], v[50:51] op_sel_hi:[1,0,1]
	ds_read_b128 v[50:53], v103
	v_pk_fma_f32 v[54:55], v[92:93], v[62:63], v[54:55] op_sel:[0,1,0]
	v_pk_fma_f32 v[58:59], v[92:93], v[66:67], v[58:59] op_sel:[0,1,0]
	s_waitcnt lgkmcnt(2)
; #define LAS __attribute__((address_space(3)))
; __device__ __forceinline__ void phase0(CArgs a, LAS unsigned char* lds, int tid, int lane, int wave, int G, int bx) {
;     ...
;                 for (int q = 0; q < 4; ++q) {
; #pragma unroll
;                     for (int r = 0; r < NB; ++r) { const f32x4 s4 = *(const LAS f32x4*)(S + r * 1024 + k + 4 * q);
;                         acc[r] += wv[4 * q] * s4[0]; acc[r] += wv[4 * q + 1] * s4[1]; acc[r] += wv[4 * q + 2] * s4[2]; acc[r] += wv[4 * q + 3] * s4[3]; } }
	v_pk_fma_f32 v[62:63], v[90:91], v[42:43], v[152:153] op_sel_hi:[1,0,1]
	v_pk_fma_f32 v[116:117], v[94:95], v[64:65], v[54:55] op_sel_hi:[1,0,1]
	ds_read_b128 v[54:57], v104
	v_pk_fma_f32 v[120:121], v[94:95], v[68:69], v[58:59] op_sel_hi:[1,0,1]
	v_pk_fma_f32 v[58:59], v[90:91], v[70:71], v[74:75] op_sel_hi:[1,0,1]
	v_pk_fma_f32 v[42:43], v[92:93], v[42:43], v[62:63] op_sel:[0,1,0]
	v_pk_fma_f32 v[58:59], v[92:93], v[70:71], v[58:59] op_sel:[0,1,0]
	v_pk_fma_f32 v[128:129], v[94:95], v[44:45], v[42:43] op_sel_hi:[1,0,1]
	s_waitcnt lgkmcnt(2)
	v_pk_fma_f32 v[42:43], v[90:91], v[46:47], v[150:151] op_sel_hi:[1,0,1]
	v_pk_fma_f32 v[126:127], v[94:95], v[72:73], v[58:59] op_sel_hi:[1,0,1]
	ds_read_b128 v[58:61], v105
	ds_read_b128 v[62:65], v106
	v_pk_fma_f32 v[42:43], v[92:93], v[46:47], v[42:43] op_sel:[0,1,0]
	s_waitcnt lgkmcnt(3)
	v_mov_b32_e32 v82, v53
	v_pk_fma_f32 v[104:105], v[94:95], v[48:49], v[42:43] op_sel_hi:[1,0,1]
	v_pk_fma_f32 v[42:43], v[90:91], v[50:51], v[148:149] op_sel_hi:[1,0,1]
	v_mov_b32_e32 v106, v49
	v_pk_fma_f32 v[42:43], v[92:93], v[50:51], v[42:43] op_sel:[0,1,0]
	s_waitcnt lgkmcnt(0)
	v_pk_fma_f32 v[48:49], v[90:91], v[62:63], v[142:143] op_sel_hi:[1,0,1]
	v_pk_fma_f32 v[84:85], v[94:95], v[52:53], v[42:43] op_sel_hi:[1,0,1]
	v_pk_fma_f32 v[42:43], v[90:91], v[54:55], v[146:147] op_sel_hi:[1,0,1]
	ds_read_b128 v[50:53], v107
	ds_read_b128 v[66:69], v111
	v_pk_fma_f32 v[42:43], v[92:93], v[54:55], v[42:43] op_sel:[0,1,0]
	v_mov_b32_e32 v130, v45
	v_pk_fma_f32 v[78:79], v[94:95], v[56:57], v[42:43] op_sel_hi:[1,0,1]
	v_pk_fma_f32 v[42:43], v[90:91], v[58:59], v[144:145] op_sel_hi:[1,0,1]
	v_mov_b32_e32 v46, v61
	v_pk_fma_f32 v[42:43], v[92:93], v[58:59], v[42:43] op_sel:[0,1,0]
	v_pk_fma_f32 v[48:49], v[92:93], v[62:63], v[48:49] op_sel:[0,1,0]
	v_pk_fma_f32 v[44:45], v[94:95], v[60:61], v[42:43] op_sel_hi:[1,0,1]
	ds_read_b128 v[60:63], v113
	ds_read_b128 v[70:73], v119
	s_waitcnt lgkmcnt(3)
	v_pk_fma_f32 v[54:55], v[90:91], v[50:51], v[140:141] op_sel_hi:[1,0,1]
	v_mov_b32_e32 v80, v57
	v_pk_fma_f32 v[50:51], v[92:93], v[50:51], v[54:55] op_sel:[0,1,0]
	v_mov_b32_e32 v54, v53
	v_pk_fma_f32 v[50:51], v[94:95], v[52:53], v[50:51] op_sel_hi:[1,0,1]
	s_waitcnt lgkmcnt(2)
	v_pk_fma_f32 v[52:53], v[90:91], v[66:67], v[134:135] op_sel_hi:[1,0,1]
	s_waitcnt lgkmcnt(1)
	v_pk_fma_f32 v[2:3], v[90:91], v[60:61], v[2:3] op_sel_hi:[1,0,1]
	s_waitcnt lgkmcnt(0)
	v_pk_fma_f32 v[0:1], v[90:91], v[70:71], v[0:1] op_sel_hi:[1,0,1]
	v_pk_fma_f32 v[52:53], v[92:93], v[66:67], v[52:53] op_sel:[0,1,0]
	v_pk_fma_f32 v[2:3], v[92:93], v[60:61], v[2:3] op_sel:[0,1,0]
	v_pk_fma_f32 v[0:1], v[92:93], v[70:71], v[0:1] op_sel:[0,1,0]
	v_pk_fma_f32 v[56:57], v[94:95], v[68:69], v[52:53] op_sel_hi:[1,0,1]
	v_mov_b32_e32 v52, v63
	v_pk_fma_f32 v[60:61], v[94:95], v[62:63], v[2:3] op_sel_hi:[1,0,1]
	ds_read_b128 v[74:77], v123
	v_pk_fma_f32 v[62:63], v[94:95], v[72:73], v[0:1] op_sel_hi:[1,0,1]
	ds_read_b128 v[0:3], v125
	v_mov_b32_e32 v42, v65
	v_pk_fma_f32 v[48:49], v[94:95], v[64:65], v[48:49] op_sel_hi:[1,0,1]
	v_mov_b32_e32 v66, v73
	s_waitcnt lgkmcnt(1)
	v_pk_fma_f32 v[64:65], v[90:91], v[74:75], v[138:139] op_sel_hi:[1,0,1]
	s_waitcnt lgkmcnt(0)
	v_pk_fma_f32 v[72:73], v[90:91], v[0:1], v[136:137] op_sel_hi:[1,0,1]
	v_pk_fma_f32 v[64:65], v[92:93], v[74:75], v[64:65] op_sel:[0,1,0]
	v_pk_fma_f32 v[0:1], v[92:93], v[0:1], v[72:73] op_sel:[0,1,0]
	v_mov_b32_e32 v58, v69
	v_pk_fma_f32 v[68:69], v[94:95], v[76:77], v[64:65] op_sel_hi:[1,0,1]
	v_mov_b32_e32 v70, v77
	v_mov_b32_e32 v64, v3
	v_pk_fma_f32 v[72:73], v[94:95], v[2:3], v[0:1] op_sel_hi:[1,0,1]
	ds_read_b128 v[74:77], v131
	ds_read_b128 v[0:3], v154
	v_pk_fma_f32 v[174:175], v[34:35], v[42:43], v[48:49] op_sel_hi:[1,0,1]
	v_mov_b32_e32 v42, s8
	v_pk_fma_f32 v[98:99], v[34:35], v[124:125], v[120:121] op_sel_hi:[1,0,1]
	s_waitcnt lgkmcnt(1)
	v_pk_fma_f32 v[132:133], v[90:91], v[74:75], v[132:133] op_sel_hi:[1,0,1]
	s_waitcnt lgkmcnt(0)
	v_pk_fma_f32 v[40:41], v[90:91], v[0:1], v[40:41] op_sel_hi:[1,0,1]
	v_pk_fma_f32 v[74:75], v[92:93], v[74:75], v[132:133] op_sel:[0,1,0]
	v_pk_fma_f32 v[0:1], v[92:93], v[0:1], v[40:41] op_sel:[0,1,0]
	v_mov_b32_e32 v40, s7
	v_pk_fma_f32 v[0:1], v[94:95], v[2:3], v[0:1] op_sel_hi:[1,0,1]
	v_mov_b32_e32 v2, v3
	v_mov_b32_e32 v3, s6
	ds_read_b128 v[132:135], v3
	ds_read_b128 v[136:139], v40
	s_add_i32 s6, s3, 0xffff6fd0
	s_add_i32 s7, s3, 0xffff7fd0
	v_mov_b32_e32 v3, s6
	s_waitcnt lgkmcnt(1)
	v_pk_fma_f32 v[38:39], v[90:91], v[132:133], v[38:39] op_sel_hi:[1,0,1]
	s_waitcnt lgkmcnt(0)
	v_pk_fma_f32 v[36:37], v[90:91], v[136:137], v[36:37] op_sel_hi:[1,0,1]
	v_pk_fma_f32 v[38:39], v[92:93], v[132:133], v[38:39] op_sel:[0,1,0]
	v_pk_fma_f32 v[36:37], v[92:93], v[136:137], v[36:37] op_sel:[0,1,0]
	v_pk_fma_f32 v[38:39], v[94:95], v[134:135], v[38:39] op_sel_hi:[1,0,1]
	v_mov_b32_e32 v40, v135
	v_pk_fma_f32 v[36:37], v[94:95], v[138:139], v[36:37] op_sel_hi:[1,0,1]
	v_mov_b32_e32 v132, v139
	v_mov_b32_e32 v41, s7
	ds_read_b128 v[134:137], v3
	ds_read_b128 v[138:141], v41
	s_add_i32 s6, s3, 0xffff8fd0
	s_add_i32 s7, s3, 0xffff9fd0
	v_mov_b32_e32 v3, s6
	s_waitcnt lgkmcnt(1)
	v_pk_fma_f32 v[32:33], v[90:91], v[134:135], v[32:33] op_sel_hi:[1,0,1]
	s_waitcnt lgkmcnt(0)
	v_pk_fma_f32 v[30:31], v[90:91], v[138:139], v[30:31] op_sel_hi:[1,0,1]
	v_pk_fma_f32 v[32:33], v[92:93], v[134:135], v[32:33] op_sel:[0,1,0]
	v_pk_fma_f32 v[30:31], v[92:93], v[138:139], v[30:31] op_sel:[0,1,0]
	v_pk_fma_f32 v[32:33], v[94:95], v[136:137], v[32:33] op_sel_hi:[1,0,1]
	v_pk_fma_f32 v[30:31], v[94:95], v[140:141], v[30:31] op_sel_hi:[1,0,1]
	v_mov_b32_e32 v136, v141
	v_mov_b32_e32 v41, s7
	ds_read_b128 v[138:141], v3
	ds_read_b128 v[142:145], v41
	s_add_i32 s6, s3, 0xffffafd0
	s_add_i32 s7, s3, 0xffffbfd0
	v_mov_b32_e32 v3, s6
	s_waitcnt lgkmcnt(1)
; #define LAS __attribute__((address_space(3)))
; __device__ __forceinline__ void phase0(CArgs a, LAS unsigned char* lds, int tid, int lane, int wave, int G, int bx) {
;     ...
;                 for (int q = 0; q < 4; ++q) {
; #pragma unroll
;                     for (int r = 0; r < NB; ++r) { const f32x4 s4 = *(const LAS f32x4*)(S + r * 1024 + k + 4 * q);
;                         acc[r] += wv[4 * q] * s4[0]; acc[r] += wv[4 * q + 1] * s4[1]; acc[r] += wv[4 * q + 2] * s4[2]; acc[r] += wv[4 * q + 3] * s4[3]; } }
	v_pk_fma_f32 v[28:29], v[90:91], v[138:139], v[28:29] op_sel_hi:[1,0,1]
	s_waitcnt lgkmcnt(0)
	v_pk_fma_f32 v[26:27], v[90:91], v[142:143], v[26:27] op_sel_hi:[1,0,1]
	v_pk_fma_f32 v[28:29], v[92:93], v[138:139], v[28:29] op_sel:[0,1,0]
	v_pk_fma_f32 v[26:27], v[92:93], v[142:143], v[26:27] op_sel:[0,1,0]
	v_pk_fma_f32 v[28:29], v[94:95], v[140:141], v[28:29] op_sel_hi:[1,0,1]
	v_pk_fma_f32 v[26:27], v[94:95], v[144:145], v[26:27] op_sel_hi:[1,0,1]
	v_mov_b32_e32 v140, v145
	v_mov_b32_e32 v41, s7
	ds_read_b128 v[142:145], v3
	ds_read_b128 v[146:149], v41
	s_add_i32 s6, s3, 0xffffcfd0
	s_add_i32 s7, s3, 0xffffdfd0
	v_mov_b32_e32 v3, s6
	s_waitcnt lgkmcnt(1)
	v_pk_fma_f32 v[24:25], v[90:91], v[142:143], v[24:25] op_sel_hi:[1,0,1]
	s_waitcnt lgkmcnt(0)
	v_pk_fma_f32 v[22:23], v[90:91], v[146:147], v[22:23] op_sel_hi:[1,0,1]
	v_pk_fma_f32 v[24:25], v[92:93], v[142:143], v[24:25] op_sel:[0,1,0]
	v_pk_fma_f32 v[22:23], v[92:93], v[146:147], v[22:23] op_sel:[0,1,0]
	v_pk_fma_f32 v[24:25], v[94:95], v[144:145], v[24:25] op_sel_hi:[1,0,1]
	v_pk_fma_f32 v[22:23], v[94:95], v[148:149], v[22:23] op_sel_hi:[1,0,1]
	v_mov_b32_e32 v144, v149
	v_mov_b32_e32 v41, s7
	ds_read_b128 v[146:149], v3
	ds_read_b128 v[150:153], v41
	s_add_i32 s6, s3, 0xffffefd0
	s_sub_i32 s7, s3, 48
	v_mov_b32_e32 v3, s6
	s_waitcnt lgkmcnt(1)
	v_pk_fma_f32 v[20:21], v[90:91], v[146:147], v[20:21] op_sel_hi:[1,0,1]
	s_waitcnt lgkmcnt(0)
	v_pk_fma_f32 v[18:19], v[90:91], v[150:151], v[18:19] op_sel_hi:[1,0,1]
	v_pk_fma_f32 v[20:21], v[92:93], v[146:147], v[20:21] op_sel:[0,1,0]
	v_pk_fma_f32 v[18:19], v[92:93], v[150:151], v[18:19] op_sel:[0,1,0]
	v_pk_fma_f32 v[20:21], v[94:95], v[148:149], v[20:21] op_sel_hi:[1,0,1]
	v_pk_fma_f32 v[18:19], v[94:95], v[152:153], v[18:19] op_sel_hi:[1,0,1]
	v_mov_b32_e32 v148, v153
	v_mov_b32_e32 v41, s7
	ds_read_b128 v[152:155], v3
	ds_read_b128 v[168:171], v41
	s_mov_b32 s6, 0xfff7c000
	v_mov_b32_e32 v138, v141
	s_add_i32 s7, s3, 0xfffdffe0
	s_waitcnt lgkmcnt(1)
	v_pk_fma_f32 v[16:17], v[90:91], v[152:153], v[16:17] op_sel_hi:[1,0,1]
	s_waitcnt lgkmcnt(0)
	v_pk_fma_f32 v[14:15], v[90:91], v[168:169], v[14:15] op_sel_hi:[1,0,1]
	v_pk_fma_f32 v[90:91], v[34:35], v[96:97], v[86:87] op_sel_hi:[1,0,1]
	v_pk_fma_f32 v[14:15], v[92:93], v[168:169], v[14:15] op_sel:[0,1,0]
	v_pk_fma_f32 v[168:169], v[34:35], v[82:83], v[84:85] op_sel_hi:[1,0,1]
	v_pk_fma_f32 v[158:159], v[94:95], v[170:171], v[14:15] op_sel_hi:[1,0,1]
	v_add_co_u32_e32 v14, vcc, s6, v12
	s_mov_b32 s6, 0xfff88000
	s_nop 0
	v_addc_co_u32_e32 v15, vcc, -1, v13, vcc
	v_add_co_u32_e32 v96, vcc, s6, v12
	s_mov_b32 s6, 0xfff94000
	s_nop 0
	v_addc_co_u32_e32 v97, vcc, -1, v13, vcc
	v_add_co_u32_e32 v82, vcc, s6, v12
	s_mov_b32 s6, 0xfffa0000
	s_nop 0
	v_addc_co_u32_e32 v83, vcc, -1, v13, vcc
	v_add_co_u32_e32 v84, vcc, s6, v12
	v_mov_b32_e32 v160, v171
	v_pk_fma_f32 v[170:171], v[34:35], v[80:81], v[78:79] op_sel_hi:[1,0,1]
	v_addc_co_u32_e32 v85, vcc, -1, v13, vcc
	s_nop 0
	s_nop 0
	s_add_i32 s6, s3, 0xfffdefe0
	v_pk_fma_f32 v[16:17], v[92:93], v[152:153], v[16:17] op_sel:[0,1,0]
	v_mov_b32_e32 v3, s6
	v_pk_fma_f32 v[152:153], v[94:95], v[154:155], v[16:17] op_sel_hi:[1,0,1]
	v_pk_fma_f32 v[16:17], v[34:35], v[130:131], v[128:129] op_sel_hi:[1,0,1]
	v_pk_fma_f32 v[130:131], v[34:35], v[2:3], v[0:1] op_sel_hi:[1,0,1]
	ds_read_b128 v[0:3], v3
	v_pk_fma_f32 v[74:75], v[94:95], v[76:77], v[74:75] op_sel_hi:[1,0,1]
	v_mov_b32_e32 v134, v137
	v_pk_fma_f32 v[94:95], v[34:35], v[118:119], v[116:117] op_sel_hi:[1,0,1]
	v_mov_b32_e32 v41, s7
	v_pk_fma_f32 v[120:121], v[34:35], v[138:139], v[28:29] op_sel_hi:[1,0,1]
	v_pk_fma_f32 v[118:119], v[34:35], v[140:141], v[26:27] op_sel_hi:[1,0,1]
	ds_read_b128 v[26:29], v42
	v_pk_fma_f32 v[86:87], v[34:35], v[112:113], v[108:109] op_sel_hi:[1,0,1]
	v_pk_fma_f32 v[108:109], v[34:35], v[122:123], v[126:127] op_sel_hi:[1,0,1]
	v_mov_b32_e32 v43, s9
	v_mov_b32_e32 v133, s31
	v_pk_fma_f32 v[124:125], v[34:35], v[134:135], v[32:33] op_sel_hi:[1,0,1]
	v_pk_fma_f32 v[122:123], v[34:35], v[136:137], v[30:31] op_sel_hi:[1,0,1]
	ds_read_b128 v[30:33], v41
	v_pk_fma_f32 v[128:129], v[34:35], v[40:41], v[38:39] op_sel_hi:[1,0,1]
	v_pk_fma_f32 v[126:127], v[34:35], v[132:133], v[36:37] op_sel_hi:[1,0,1]
	ds_read_b128 v[36:39], v43
	v_mov_b32_e32 v146, v149
	v_pk_fma_f32 v[172:173], v[34:35], v[46:47], v[44:45] op_sel_hi:[1,0,1]
	v_mov_b32_e32 v44, s14
	v_pk_fma_f32 v[88:89], v[34:35], v[102:103], v[100:101] op_sel_hi:[1,0,1]
	v_pk_fma_f32 v[92:93], v[34:35], v[110:111], v[114:115] op_sel_hi:[1,0,1]
	v_pk_fma_f32 v[114:115], v[34:35], v[144:145], v[22:23] op_sel_hi:[1,0,1]
	v_pk_fma_f32 v[112:113], v[34:35], v[146:147], v[20:21] op_sel_hi:[1,0,1]
	ds_read_b128 v[20:23], v44
	v_pk_fma_f32 v[110:111], v[34:35], v[148:149], v[18:19] op_sel_hi:[1,0,1]
	v_mov_b32_e32 v45, s15
	v_pk_fma_f32 v[184:185], v[34:35], v[66:67], v[62:63] op_sel_hi:[1,0,1]
	ds_read_b128 v[40:43], v45
	v_mov_b32_e32 v46, s16
	v_mov_b32_e32 v48, s17
	v_pk_fma_f32 v[182:183], v[34:35], v[52:53], v[60:61] op_sel_hi:[1,0,1]
	v_mov_b32_e32 v52, s18
	v_pk_fma_f32 v[188:189], v[34:35], v[64:65], v[72:73] op_sel_hi:[1,0,1]
	v_mov_b32_e32 v142, v145
	v_pk_fma_f32 v[176:177], v[34:35], v[54:55], v[50:51] op_sel_hi:[1,0,1]
	v_mov_b32_e32 v53, s19
	v_pk_fma_f32 v[186:187], v[34:35], v[70:71], v[68:69] op_sel_hi:[1,0,1]
	ds_read_b128 v[44:47], v46
	ds_read_b128 v[48:51], v48
	s_waitcnt lgkmcnt(7)
	v_mov_b32_e32 v66, v3
	v_pk_fma_f32 v[116:117], v[34:35], v[142:143], v[24:25] op_sel_hi:[1,0,1]
	v_mov_b32_e32 v54, s20
	v_mov_b32_e32 v76, v77
	v_mov_b32_e32 v55, s21
	v_pk_fma_f32 v[150:151], v[34:35], v[106:107], v[104:105] op_sel_hi:[1,0,1]
	v_pk_fma_f32 v[190:191], v[34:35], v[76:77], v[74:75] op_sel_hi:[1,0,1]
	s_waitcnt lgkmcnt(6)
; #define LAS __attribute__((address_space(3)))
; __device__ __forceinline__ void phase0(CArgs a, LAS unsigned char* lds, int tid, int lane, int wave, int G, int bx) {
;     ...
;                 for (int i = 0; i < 16; ++i) wv[i] = __builtin_nontemporal_load((const f32x2*)(wp + (size_t)i * NMOD));
; #pragma unroll
;                 for (int q = 0; q < 4; ++q) {
; #pragma unroll
;                     for (int r = 0; r < NB; ++r) { const f32x4 s4 = *(const LAS f32x4*)(S + r * 1024 + k + 4 * q);
;                         acc[r] += wv[4 * q] * s4[0]; acc[r] += wv[4 * q + 1] * s4[1]; acc[r] += wv[4 * q + 2] * s4[2]; acc[r] += wv[4 * q + 3] * s4[3]; } }
	v_mov_b32_e32 v74, v29
	v_mov_b32_e32 v154, v155
	v_pk_fma_f32 v[180:181], v[34:35], v[58:59], v[56:57] op_sel_hi:[1,0,1]
	v_mov_b32_e32 v56, s22
	v_mov_b32_e32 v57, s23
	v_pk_fma_f32 v[68:69], v[34:35], v[154:155], v[152:153] op_sel_hi:[1,0,1]
	v_pk_fma_f32 v[60:61], v[34:35], v[160:161], v[158:159] op_sel_hi:[1,0,1]
	s_waitcnt lgkmcnt(5)
	v_mov_b32_e32 v64, v33
	v_mov_b32_e32 v65, s24
	v_mov_b32_e32 v67, s25
	v_mov_b32_e32 v75, s26
	v_mov_b32_e32 v85, s27
	s_waitcnt lgkmcnt(2)
	v_mov_b32_e32 v96, v43
	v_mov_b32_e32 v97, s28
	v_mov_b32_e32 v101, s29
	s_waitcnt lgkmcnt(1)
	v_mov_b32_e32 v102, v47
	v_mov_b32_e32 v103, s30
	s_waitcnt lgkmcnt(0)
	v_mov_b32_e32 v100, v51
	s_add_i32 s6, s3, 0xffff4fe0
	s_add_i32 s7, s3, 0xffff5fe0
	s_add_i32 s8, s3, 0xfffe0ff0
	s_add_i32 s9, s3, 0xfffe1ff0
	s_add_i32 s14, s3, 0xfffe2ff0
	s_waitcnt vmcnt(15)
	v_mov_b32_e32 v78, v228
	v_mov_b32_e32 v79, v229
	s_mov_b32 s44, 0xfff7c000
	v_lshl_add_u64 v[206:207], v[208:209], 0, s[44:45]
	global_load_dwordx2 v[228:229], v[206:207], off nt
	v_pk_fma_f32 v[18:19], v[78:79], v[0:1], v[156:157] op_sel_hi:[1,0,1]
	s_add_i32 s15, s3, 0xfffe3ff0
	s_waitcnt vmcnt(15)
	v_mov_b32_e32 v80, v230
	v_mov_b32_e32 v81, v231
	s_mov_b32 s44, 0xfff88000
	v_lshl_add_u64 v[206:207], v[208:209], 0, s[44:45]
	global_load_dwordx2 v[230:231], v[206:207], off nt
	v_pk_fma_f32 v[0:1], v[80:81], v[0:1], v[18:19] op_sel:[0,1,0]
	v_pk_fma_f32 v[18:19], v[78:79], v[26:27], v[88:89] op_sel_hi:[1,0,1]
	s_waitcnt vmcnt(15)
	v_mov_b32_e32 v82, v232
	v_mov_b32_e32 v83, v233
	s_mov_b32 s44, 0xfff94000
	v_lshl_add_u64 v[206:207], v[208:209], 0, s[44:45]
	global_load_dwordx2 v[232:233], v[206:207], off nt
	v_pk_fma_f32 v[62:63], v[82:83], v[2:3], v[0:1] op_sel_hi:[1,0,1]
	v_pk_fma_f32 v[0:1], v[78:79], v[30:31], v[90:91] op_sel_hi:[1,0,1]
	v_pk_fma_f32 v[18:19], v[80:81], v[26:27], v[18:19] op_sel:[0,1,0]
	v_pk_fma_f32 v[0:1], v[80:81], v[30:31], v[0:1] op_sel:[0,1,0]
	v_pk_fma_f32 v[72:73], v[82:83], v[28:29], v[18:19] op_sel_hi:[1,0,1]
	v_pk_fma_f32 v[18:19], v[78:79], v[36:37], v[86:87] op_sel_hi:[1,0,1]
	v_pk_fma_f32 v[70:71], v[82:83], v[32:33], v[0:1] op_sel_hi:[1,0,1]
	ds_read_b128 v[0:3], v52
	ds_read_b128 v[24:27], v53
	v_pk_fma_f32 v[18:19], v[80:81], v[36:37], v[18:19] op_sel:[0,1,0]
	v_mov_b32_e32 v88, v23
	v_pk_fma_f32 v[86:87], v[82:83], v[38:39], v[18:19] op_sel_hi:[1,0,1]
	v_pk_fma_f32 v[18:19], v[78:79], v[20:21], v[92:93] op_sel_hi:[1,0,1]
	ds_read_b128 v[28:31], v55
	v_pk_fma_f32 v[18:19], v[80:81], v[20:21], v[18:19] op_sel:[0,1,0]
	s_waitcnt lgkmcnt(2)
	v_pk_fma_f32 v[16:17], v[78:79], v[0:1], v[16:17] op_sel_hi:[1,0,1]
	v_pk_fma_f32 v[92:93], v[82:83], v[22:23], v[18:19] op_sel_hi:[1,0,1]
	ds_read_b128 v[18:21], v54
	v_pk_fma_f32 v[22:23], v[78:79], v[40:41], v[94:95] op_sel_hi:[1,0,1]
	v_pk_fma_f32 v[0:1], v[80:81], v[0:1], v[16:17] op_sel:[0,1,0]
	v_pk_fma_f32 v[22:23], v[80:81], v[40:41], v[22:23] op_sel:[0,1,0]
	s_waitcnt lgkmcnt(2)
	v_pk_fma_f32 v[16:17], v[78:79], v[24:25], v[150:151] op_sel_hi:[1,0,1]
	v_pk_fma_f32 v[94:95], v[82:83], v[42:43], v[22:23] op_sel_hi:[1,0,1]
	v_pk_fma_f32 v[22:23], v[78:79], v[44:45], v[98:99] op_sel_hi:[1,0,1]
	ds_read_b128 v[32:35], v56
	v_pk_fma_f32 v[22:23], v[80:81], v[44:45], v[22:23] op_sel:[0,1,0]
	v_pk_fma_f32 v[106:107], v[82:83], v[2:3], v[0:1] op_sel_hi:[1,0,1]
	v_pk_fma_f32 v[98:99], v[82:83], v[46:47], v[22:23] op_sel_hi:[1,0,1]
	v_pk_fma_f32 v[22:23], v[78:79], v[48:49], v[108:109] op_sel_hi:[1,0,1]
	v_mov_b32_e32 v108, v3
	ds_read_b128 v[0:3], v57
	v_pk_fma_f32 v[16:17], v[80:81], v[24:25], v[16:17] op_sel:[0,1,0]
	v_pk_fma_f32 v[22:23], v[80:81], v[48:49], v[22:23] op_sel:[0,1,0]
	v_pk_fma_f32 v[76:77], v[82:83], v[26:27], v[16:17] op_sel_hi:[1,0,1]
	s_waitcnt lgkmcnt(2)
	v_pk_fma_f32 v[16:17], v[78:79], v[18:19], v[168:169] op_sel_hi:[1,0,1]
	v_pk_fma_f32 v[104:105], v[82:83], v[50:51], v[22:23] op_sel_hi:[1,0,1]
	v_pk_fma_f32 v[16:17], v[80:81], v[18:19], v[16:17] op_sel:[0,1,0]
	v_mov_b32_e32 v84, v27
	v_pk_fma_f32 v[58:59], v[82:83], v[20:21], v[16:17] op_sel_hi:[1,0,1]
	v_pk_fma_f32 v[16:17], v[78:79], v[28:29], v[170:171] op_sel_hi:[1,0,1]
	ds_read_b128 v[24:27], v65
	v_pk_fma_f32 v[16:17], v[80:81], v[28:29], v[16:17] op_sel:[0,1,0]
	s_waitcnt lgkmcnt(1)
	v_pk_fma_f32 v[22:23], v[78:79], v[0:1], v[174:175] op_sel_hi:[1,0,1]
	v_pk_fma_f32 v[52:53], v[82:83], v[30:31], v[16:17] op_sel_hi:[1,0,1]
	v_pk_fma_f32 v[16:17], v[78:79], v[32:33], v[172:173] op_sel_hi:[1,0,1]
	v_pk_fma_f32 v[0:1], v[80:81], v[0:1], v[22:23] op_sel:[0,1,0]
	v_pk_fma_f32 v[16:17], v[80:81], v[32:33], v[16:17] op_sel:[0,1,0]
	v_mov_b32_e32 v90, v39
	ds_read_b128 v[36:39], v67
	v_pk_fma_f32 v[18:19], v[82:83], v[34:35], v[16:17] op_sel_hi:[1,0,1]
	v_mov_b32_e32 v16, v3
	v_pk_fma_f32 v[22:23], v[82:83], v[2:3], v[0:1] op_sel_hi:[1,0,1]
	ds_read_b128 v[0:3], v75
	ds_read_b128 v[40:43], v85
	s_waitcnt lgkmcnt(3)
	v_pk_fma_f32 v[28:29], v[78:79], v[24:25], v[176:177] op_sel_hi:[1,0,1]
	v_mov_b32_e32 v20, v35
	v_pk_fma_f32 v[24:25], v[80:81], v[24:25], v[28:29] op_sel:[0,1,0]
	v_mov_b32_e32 v28, v27
	v_pk_fma_f32 v[24:25], v[82:83], v[26:27], v[24:25] op_sel_hi:[1,0,1]
	s_waitcnt lgkmcnt(2)
	v_pk_fma_f32 v[26:27], v[78:79], v[36:37], v[180:181] op_sel_hi:[1,0,1]
	s_waitcnt lgkmcnt(1)
	v_pk_fma_f32 v[34:35], v[78:79], v[0:1], v[182:183] op_sel_hi:[1,0,1]
	v_pk_fma_f32 v[26:27], v[80:81], v[36:37], v[26:27] op_sel:[0,1,0]
	v_pk_fma_f32 v[0:1], v[80:81], v[0:1], v[34:35] op_sel:[0,1,0]
	v_mov_b32_e32 v54, v31
	v_pk_fma_f32 v[30:31], v[82:83], v[38:39], v[26:27] op_sel_hi:[1,0,1]
	v_mov_b32_e32 v26, v3
	v_pk_fma_f32 v[34:35], v[82:83], v[2:3], v[0:1] op_sel_hi:[1,0,1]
	ds_read_b128 v[0:3], v97
	ds_read_b128 v[46:49], v101
	v_mov_b32_e32 v32, v39
	s_waitcnt lgkmcnt(2)
; #define LAS __attribute__((address_space(3)))
; __device__ __forceinline__ void phase0(CArgs a, LAS unsigned char* lds, int tid, int lane, int wave, int G, int bx) {
;     ...
;                 for (int i = 0; i < 16; ++i) wv[i] = __builtin_nontemporal_load((const f32x2*)(wp + (size_t)i * NMOD));
; #pragma unroll
;                 for (int q = 0; q < 4; ++q) {
; #pragma unroll
;                     for (int r = 0; r < NB; ++r) { const f32x4 s4 = *(const LAS f32x4*)(S + r * 1024 + k + 4 * q);
;                         acc[r] += wv[4 * q] * s4[0]; acc[r] += wv[4 * q + 1] * s4[1]; acc[r] += wv[4 * q + 2] * s4[2]; acc[r] += wv[4 * q + 3] * s4[3]; } }
	v_pk_fma_f32 v[36:37], v[78:79], v[40:41], v[184:185] op_sel_hi:[1,0,1]
	v_mov_b32_e32 v56, v21
	s_waitcnt lgkmcnt(1)
	v_pk_fma_f32 v[38:39], v[78:79], v[0:1], v[186:187] op_sel_hi:[1,0,1]
	v_pk_fma_f32 v[36:37], v[80:81], v[40:41], v[36:37] op_sel:[0,1,0]
	v_pk_fma_f32 v[0:1], v[80:81], v[0:1], v[38:39] op_sel:[0,1,0]
	v_pk_fma_f32 v[36:37], v[82:83], v[42:43], v[36:37] op_sel_hi:[1,0,1]
	v_mov_b32_e32 v40, v43
	v_pk_fma_f32 v[42:43], v[82:83], v[2:3], v[0:1] op_sel_hi:[1,0,1]
	s_waitcnt lgkmcnt(0)
	v_pk_fma_f32 v[0:1], v[78:79], v[46:47], v[188:189] op_sel_hi:[1,0,1]
	v_mov_b32_e32 v44, v3
	v_pk_fma_f32 v[0:1], v[80:81], v[46:47], v[0:1] op_sel:[0,1,0]
	v_mov_b32_e32 v38, v49
	v_pk_fma_f32 v[46:47], v[82:83], v[48:49], v[0:1] op_sel_hi:[1,0,1]
	ds_read_b128 v[48:51], v103
	ds_read_b128 v[0:3], v133
	s_waitcnt vmcnt(15)
	v_mov_b32_e32 v14, v234
	v_mov_b32_e32 v15, v235
	s_mov_b32 s44, 0xfffa0000
	v_lshl_add_u64 v[206:207], v[208:209], 0, s[44:45]
	global_load_dwordx2 v[234:235], v[206:207], off nt
	v_pk_fma_f32 v[58:59], v[14:15], v[56:57], v[58:59] op_sel_hi:[1,0,1]
	v_pk_fma_f32 v[54:55], v[14:15], v[54:55], v[52:53] op_sel_hi:[1,0,1]
	v_pk_fma_f32 v[168:169], v[14:15], v[66:67], v[62:63] op_sel_hi:[1,0,1]
	s_waitcnt lgkmcnt(1)
	v_pk_fma_f32 v[132:133], v[78:79], v[48:49], v[190:191] op_sel_hi:[1,0,1]
	s_waitcnt lgkmcnt(0)
	v_pk_fma_f32 v[130:131], v[78:79], v[0:1], v[130:131] op_sel_hi:[1,0,1]
	v_pk_fma_f32 v[48:49], v[80:81], v[48:49], v[132:133] op_sel:[0,1,0]
	v_pk_fma_f32 v[0:1], v[80:81], v[0:1], v[130:131] op_sel:[0,1,0]
	v_pk_fma_f32 v[62:63], v[14:15], v[100:101], v[104:105] op_sel_hi:[1,0,1]
	v_pk_fma_f32 v[130:131], v[82:83], v[2:3], v[0:1] op_sel_hi:[1,0,1]
	v_mov_b32_e32 v0, s6
	v_mov_b32_e32 v1, s7
	ds_read_b128 v[132:135], v0
	ds_read_b128 v[136:139], v1
	s_add_i32 s6, s3, 0xffff6fe0
	s_add_i32 s7, s3, 0xffff7fe0
	v_mov_b32_e32 v2, v3
	s_waitcnt lgkmcnt(1)
	v_pk_fma_f32 v[0:1], v[78:79], v[132:133], v[128:129] op_sel_hi:[1,0,1]
	v_mov_b32_e32 v27, s8
	v_pk_fma_f32 v[0:1], v[80:81], v[132:133], v[0:1] op_sel:[0,1,0]
	v_mov_b32_e32 v29, s9
	v_pk_fma_f32 v[128:129], v[82:83], v[134:135], v[0:1] op_sel_hi:[1,0,1]
	s_waitcnt lgkmcnt(0)
	v_pk_fma_f32 v[0:1], v[78:79], v[136:137], v[126:127] op_sel_hi:[1,0,1]
	v_mov_b32_e32 v134, v139
	v_pk_fma_f32 v[0:1], v[80:81], v[136:137], v[0:1] op_sel:[0,1,0]
	v_pk_fma_f32 v[176:177], v[14:15], v[26:27], v[34:35] op_sel_hi:[1,0,1]
	v_pk_fma_f32 v[126:127], v[82:83], v[138:139], v[0:1] op_sel_hi:[1,0,1]
	v_mov_b32_e32 v0, s6
	v_mov_b32_e32 v1, s7
	ds_read_b128 v[136:139], v0
	ds_read_b128 v[140:143], v1
	s_add_i32 s6, s3, 0xffff8fe0
	s_add_i32 s7, s3, 0xffff9fe0
	v_mov_b32_e32 v33, s14
	s_waitcnt lgkmcnt(1)
	v_pk_fma_f32 v[0:1], v[78:79], v[136:137], v[124:125] op_sel_hi:[1,0,1]
	v_pk_fma_f32 v[174:175], v[14:15], v[32:33], v[30:31] op_sel_hi:[1,0,1]
	v_pk_fma_f32 v[0:1], v[80:81], v[136:137], v[0:1] op_sel:[0,1,0]
	s_add_i32 s16, s3, 0xfffe4ff0
	v_pk_fma_f32 v[124:125], v[82:83], v[138:139], v[0:1] op_sel_hi:[1,0,1]
	s_waitcnt lgkmcnt(0)
	v_pk_fma_f32 v[0:1], v[78:79], v[140:141], v[122:123] op_sel_hi:[1,0,1]
	v_mov_b32_e32 v138, v143
	v_pk_fma_f32 v[0:1], v[80:81], v[140:141], v[0:1] op_sel:[0,1,0]
	v_pk_fma_f32 v[48:49], v[82:83], v[50:51], v[48:49] op_sel_hi:[1,0,1]
	v_pk_fma_f32 v[122:123], v[82:83], v[142:143], v[0:1] op_sel_hi:[1,0,1]
	v_mov_b32_e32 v0, s6
	v_mov_b32_e32 v1, s7
	ds_read_b128 v[140:143], v0
	ds_read_b128 v[144:147], v1
	s_add_i32 s6, s3, 0xffffafe0
	s_add_i32 s7, s3, 0xffffbfe0
	s_add_i32 s21, s3, 0xfffe9ff0
	s_waitcnt lgkmcnt(1)
	v_pk_fma_f32 v[0:1], v[78:79], v[140:141], v[120:121] op_sel_hi:[1,0,1]
	v_mov_b32_e32 v39, s15
	v_pk_fma_f32 v[0:1], v[80:81], v[140:141], v[0:1] op_sel:[0,1,0]
	v_mov_b32_e32 v41, s16
	v_pk_fma_f32 v[120:121], v[82:83], v[142:143], v[0:1] op_sel_hi:[1,0,1]
	s_waitcnt lgkmcnt(0)
	v_pk_fma_f32 v[0:1], v[78:79], v[144:145], v[118:119] op_sel_hi:[1,0,1]
	v_mov_b32_e32 v142, v147
	v_pk_fma_f32 v[0:1], v[80:81], v[144:145], v[0:1] op_sel:[0,1,0]
	v_mov_b32_e32 v132, v135
	v_pk_fma_f32 v[118:119], v[82:83], v[146:147], v[0:1] op_sel_hi:[1,0,1]
	v_mov_b32_e32 v0, s6
	v_mov_b32_e32 v1, s7
	ds_read_b128 v[144:147], v0
	ds_read_b128 v[148:151], v1
	s_add_i32 s6, s3, 0xffffcfe0
	s_add_i32 s7, s3, 0xffffdfe0
	v_pk_fma_f32 v[180:181], v[14:15], v[40:41], v[36:37] op_sel_hi:[1,0,1]
	s_waitcnt lgkmcnt(1)
	v_pk_fma_f32 v[0:1], v[78:79], v[144:145], v[116:117] op_sel_hi:[1,0,1]
	v_mov_b32_e32 v133, s21
	v_pk_fma_f32 v[0:1], v[80:81], v[144:145], v[0:1] op_sel:[0,1,0]
	v_pk_fma_f32 v[184:185], v[14:15], v[38:39], v[46:47] op_sel_hi:[1,0,1]
	v_pk_fma_f32 v[116:117], v[82:83], v[146:147], v[0:1] op_sel_hi:[1,0,1]
	s_waitcnt lgkmcnt(0)
	v_pk_fma_f32 v[0:1], v[78:79], v[148:149], v[114:115] op_sel_hi:[1,0,1]
	v_mov_b32_e32 v146, v151
	v_pk_fma_f32 v[0:1], v[80:81], v[148:149], v[0:1] op_sel:[0,1,0]
	s_add_i32 s17, s3, 0xfffe5ff0
	v_pk_fma_f32 v[114:115], v[82:83], v[150:151], v[0:1] op_sel_hi:[1,0,1]
	v_mov_b32_e32 v0, s6
	v_mov_b32_e32 v1, s7
	ds_read_b128 v[148:151], v0
	ds_read_b128 v[152:155], v1
	s_add_i32 s6, s3, 0xffffefe0
	s_sub_i32 s7, s3, 32
	v_mov_b32_e32 v136, v139
	s_waitcnt lgkmcnt(1)
	v_pk_fma_f32 v[0:1], v[78:79], v[148:149], v[112:113] op_sel_hi:[1,0,1]
	v_mov_b32_e32 v45, s17
	v_pk_fma_f32 v[0:1], v[80:81], v[148:149], v[0:1] op_sel:[0,1,0]
	v_mov_b32_e32 v148, v151
	v_pk_fma_f32 v[112:113], v[82:83], v[150:151], v[0:1] op_sel_hi:[1,0,1]
	s_waitcnt lgkmcnt(0)
; #define LAS __attribute__((address_space(3)))
; __device__ __forceinline__ void phase0(CArgs a, LAS unsigned char* lds, int tid, int lane, int wave, int G, int bx) {
;     ...
;                 for (int i = 0; i < 16; ++i) wv[i] = __builtin_nontemporal_load((const f32x2*)(wp + (size_t)i * NMOD));
; #pragma unroll
;                 for (int q = 0; q < 4; ++q) {
; #pragma unroll
;                     for (int r = 0; r < NB; ++r) { const f32x4 s4 = *(const LAS f32x4*)(S + r * 1024 + k + 4 * q);
;                         acc[r] += wv[4 * q] * s4[0]; acc[r] += wv[4 * q + 1] * s4[1]; acc[r] += wv[4 * q + 2] * s4[2]; acc[r] += wv[4 * q + 3] * s4[3]; } }
	v_pk_fma_f32 v[0:1], v[78:79], v[152:153], v[110:111] op_sel_hi:[1,0,1]
	v_mov_b32_e32 v150, v155
	v_pk_fma_f32 v[0:1], v[80:81], v[152:153], v[0:1] op_sel:[0,1,0]
	v_pk_fma_f32 v[182:183], v[14:15], v[44:45], v[42:43] op_sel_hi:[1,0,1]
	v_pk_fma_f32 v[110:111], v[82:83], v[154:155], v[0:1] op_sel_hi:[1,0,1]
	v_mov_b32_e32 v0, s6
	v_mov_b32_e32 v1, s7
	ds_read_b128 v[152:155], v0
	ds_read_b128 v[170:173], v1
	s_mov_b32 s6, 0xfffac000
	s_add_i32 s7, s3, 0xfffdfff0
	s_add_i32 s18, s3, 0xfffe6ff0
	s_waitcnt lgkmcnt(1)
	v_pk_fma_f32 v[0:1], v[78:79], v[152:153], v[68:69] op_sel_hi:[1,0,1]
	v_mov_b32_e32 v158, v155
	v_pk_fma_f32 v[0:1], v[80:81], v[152:153], v[0:1] op_sel:[0,1,0]
	v_pk_fma_f32 v[152:153], v[14:15], v[74:75], v[72:73] op_sel_hi:[1,0,1]
	v_pk_fma_f32 v[156:157], v[82:83], v[154:155], v[0:1] op_sel_hi:[1,0,1]
	s_waitcnt lgkmcnt(0)
	v_pk_fma_f32 v[0:1], v[78:79], v[170:171], v[60:61] op_sel_hi:[1,0,1]
	v_pk_fma_f32 v[154:155], v[14:15], v[64:65], v[70:71] op_sel_hi:[1,0,1]
	v_pk_fma_f32 v[0:1], v[80:81], v[170:171], v[0:1] op_sel:[0,1,0]
	v_pk_fma_f32 v[78:79], v[14:15], v[88:89], v[92:93] op_sel_hi:[1,0,1]
	v_pk_fma_f32 v[170:171], v[82:83], v[172:173], v[0:1] op_sel_hi:[1,0,1]
	v_add_co_u32_e32 v0, vcc, s6, v12
	s_mov_b32 s6, 0xfffb8000
	s_nop 0
	v_addc_co_u32_e32 v1, vcc, -1, v13, vcc
	v_add_co_u32_e32 v64, vcc, s6, v12
	s_mov_b32 s6, 0xfffc4000
	s_nop 0
	v_addc_co_u32_e32 v65, vcc, -1, v13, vcc
	v_add_co_u32_e32 v56, vcc, s6, v12
	s_mov_b32 s6, 0xfffd0000
	s_nop 0
	v_addc_co_u32_e32 v57, vcc, -1, v13, vcc
	v_add_co_u32_e32 v52, vcc, s6, v12
	s_add_i32 s6, s3, 0xfffdeff0
	s_nop 0
	v_addc_co_u32_e32 v53, vcc, -1, v13, vcc
	s_nop 0
	v_mov_b32_e32 v3, s6
	v_pk_fma_f32 v[74:75], v[14:15], v[96:97], v[94:95] op_sel_hi:[1,0,1]
	v_pk_fma_f32 v[70:71], v[14:15], v[102:103], v[98:99] op_sel_hi:[1,0,1]
	v_pk_fma_f32 v[94:95], v[14:15], v[20:21], v[18:19] op_sel_hi:[1,0,1]
	v_pk_fma_f32 v[98:99], v[14:15], v[16:17], v[22:23] op_sel_hi:[1,0,1]
	ds_read_b128 v[16:19], v3
	v_mov_b32_e32 v20, s7
	ds_read_b128 v[20:23], v20
	v_mov_b32_e32 v160, v173
	v_pk_fma_f32 v[172:173], v[14:15], v[28:29], v[24:25] op_sel_hi:[1,0,1]
	ds_read_b128 v[24:27], v27
	ds_read_b128 v[28:31], v29
	v_pk_fma_f32 v[52:53], v[14:15], v[2:3], v[130:131] op_sel_hi:[1,0,1]
	ds_read_b128 v[32:35], v33
	ds_read_b128 v[36:39], v39
	v_pk_fma_f32 v[82:83], v[14:15], v[90:91], v[86:87] op_sel_hi:[1,0,1]
	v_pk_fma_f32 v[90:91], v[14:15], v[148:149], v[112:113] op_sel_hi:[1,0,1]
	v_pk_fma_f32 v[56:57], v[14:15], v[132:133], v[128:129] op_sel_hi:[1,0,1]
	v_pk_fma_f32 v[64:65], v[14:15], v[136:137], v[124:125] op_sel_hi:[1,0,1]
	ds_read_b128 v[40:43], v41
	ds_read_b128 v[44:47], v45
	s_add_i32 s22, s3, 0xfffeaff0
	s_add_i32 s23, s3, 0xfffebff0
	s_add_i32 s24, s3, 0xfffecff0
	s_add_i32 s25, s3, 0xfffedff0
	s_add_i32 s29, s3, 0xffff1ff0
	s_add_i32 s30, s3, 0xffff2ff0
	v_mov_b32_e32 v50, v51
	v_mov_b32_e32 v140, v143
	v_mov_b32_e32 v144, v147
	v_pk_fma_f32 v[86:87], v[14:15], v[84:85], v[76:77] op_sel_hi:[1,0,1]
	v_mov_b32_e32 v51, s18
	v_mov_b32_e32 v135, s22
	v_mov_b32_e32 v139, s23
	v_mov_b32_e32 v141, s24
	v_mov_b32_e32 v147, s25
	v_mov_b32_e32 v151, s29
	v_mov_b32_e32 v159, s30
	v_pk_fma_f32 v[76:77], v[14:15], v[142:143], v[118:119] op_sel_hi:[1,0,1]
	v_pk_fma_f32 v[60:61], v[14:15], v[108:109], v[106:107] op_sel_hi:[1,0,1]
	s_add_i32 s19, s3, 0xfffe7ff0
	v_pk_fma_f32 v[186:187], v[14:15], v[50:51], v[48:49] op_sel_hi:[1,0,1]
	v_pk_fma_f32 v[66:67], v[14:15], v[134:135], v[126:127] op_sel_hi:[1,0,1]
	v_pk_fma_f32 v[68:69], v[14:15], v[138:139], v[122:123] op_sel_hi:[1,0,1]
	v_pk_fma_f32 v[72:73], v[14:15], v[140:141], v[120:121] op_sel_hi:[1,0,1]
	v_pk_fma_f32 v[80:81], v[14:15], v[144:145], v[116:117] op_sel_hi:[1,0,1]
	v_pk_fma_f32 v[84:85], v[14:15], v[146:147], v[114:115] op_sel_hi:[1,0,1]
	v_pk_fma_f32 v[96:97], v[14:15], v[150:151], v[110:111] op_sel_hi:[1,0,1]
	v_pk_fma_f32 v[110:111], v[14:15], v[158:159], v[156:157] op_sel_hi:[1,0,1]
	v_pk_fma_f32 v[102:103], v[14:15], v[160:161], v[170:171] op_sel_hi:[1,0,1]
	v_mov_b32_e32 v107, s19
	s_add_i32 s20, s3, 0xfffe8ff0
	s_waitcnt lgkmcnt(7)
	v_mov_b32_e32 v108, v19
	v_mov_b32_e32 v109, s20
	s_waitcnt lgkmcnt(6)
	v_mov_b32_e32 v106, v23
	s_waitcnt lgkmcnt(4)
	v_mov_b32_e32 v140, v31
	s_waitcnt lgkmcnt(3)
	v_mov_b32_e32 v138, v35
	v_mov_b32_e32 v132, v27
	s_add_i32 s26, s3, 0xfffeeff0
	s_waitcnt lgkmcnt(2)
	v_mov_b32_e32 v146, v39
	v_mov_b32_e32 v48, s26
	s_add_i32 s27, s3, 0xfffefff0
	s_add_i32 s28, s3, 0xffff0ff0
	v_mov_b32_e32 v49, s27
	v_mov_b32_e32 v50, s28
	s_waitcnt lgkmcnt(0)
	v_mov_b32_e32 v150, v47
	s_add_i32 s31, s3, 0xffff3ff0
	v_mov_b32_e32 v188, s31
	s_add_i32 s6, s3, 0xffff4ff0
	s_add_i32 s7, s3, 0xffff5ff0
	s_add_i32 s8, s3, 0xfffe1000
	s_add_i32 s9, s3, 0xfffe2000
	s_add_i32 s14, s3, 0xfffe3000
	s_add_i32 s17, s3, 0xfffe6000
	s_add_i32 s15, s3, 0xfffe4000
	s_add_i32 s16, s3, 0xfffe5000
	s_add_i32 s18, s3, 0xfffe7000
	s_waitcnt vmcnt(15)
	v_mov_b32_e32 v88, v236
	v_mov_b32_e32 v89, v237
	s_mov_b32 s44, 0xfffac000
	v_lshl_add_u64 v[206:207], v[208:209], 0, s[44:45]
	global_load_dwordx2 v[236:237], v[206:207], off nt
	v_pk_fma_f32 v[2:3], v[88:89], v[16:17], v[168:169] op_sel_hi:[1,0,1]
	s_add_i32 s19, s3, 0xfffe8000
	s_waitcnt vmcnt(15)
	v_mov_b32_e32 v92, v238
	v_mov_b32_e32 v93, v239
	s_mov_b32 s44, 0xfffb8000
	v_lshl_add_u64 v[206:207], v[208:209], 0, s[44:45]
	global_load_dwordx2 v[238:239], v[206:207], off nt
	v_pk_fma_f32 v[2:3], v[92:93], v[16:17], v[2:3] op_sel:[0,1,0]
	ds_read_b128 v[14:17], v51
	s_waitcnt vmcnt(15)
; #define LAS __attribute__((address_space(3)))
; __device__ __forceinline__ void phase0(CArgs a, LAS unsigned char* lds, int tid, int lane, int wave, int G, int bx) {
;     ...
;                 for (int i = 0; i < 16; ++i) wv[i] = __builtin_nontemporal_load((const f32x2*)(wp + (size_t)i * NMOD));
; #pragma unroll
;                 for (int q = 0; q < 4; ++q) {
; #pragma unroll
;                     for (int r = 0; r < NB; ++r) { const f32x4 s4 = *(const LAS f32x4*)(S + r * 1024 + k + 4 * q);
;                         acc[r] += wv[4 * q] * s4[0]; acc[r] += wv[4 * q + 1] * s4[1]; acc[r] += wv[4 * q + 2] * s4[2]; acc[r] += wv[4 * q + 3] * s4[3]; } }
	v_mov_b32_e32 v100, v240
	v_mov_b32_e32 v101, v241
	s_mov_b32 s44, 0xfffc4000
	v_lshl_add_u64 v[206:207], v[208:209], 0, s[44:45]
	global_load_dwordx2 v[240:241], v[206:207], off nt
	v_pk_fma_f32 v[104:105], v[100:101], v[18:19], v[2:3] op_sel_hi:[1,0,1]
	v_pk_fma_f32 v[2:3], v[88:89], v[20:21], v[154:155] op_sel_hi:[1,0,1]
	s_add_i32 s20, s3, 0xfffe9000
	v_pk_fma_f32 v[2:3], v[92:93], v[20:21], v[2:3] op_sel:[0,1,0]
	ds_read_b128 v[18:21], v107
	v_pk_fma_f32 v[112:113], v[100:101], v[22:23], v[2:3] op_sel_hi:[1,0,1]
	v_pk_fma_f32 v[2:3], v[88:89], v[24:25], v[152:153] op_sel_hi:[1,0,1]
	v_mov_b32_e32 v152, v43
	v_pk_fma_f32 v[2:3], v[92:93], v[24:25], v[2:3] op_sel:[0,1,0]
	ds_read_b128 v[22:25], v109
	v_pk_fma_f32 v[128:129], v[100:101], v[26:27], v[2:3] op_sel_hi:[1,0,1]
	v_pk_fma_f32 v[2:3], v[88:89], v[28:29], v[82:83] op_sel_hi:[1,0,1]
	s_waitcnt lgkmcnt(2)
	v_mov_b32_e32 v158, v17
	v_pk_fma_f32 v[2:3], v[92:93], v[28:29], v[2:3] op_sel:[0,1,0]
	ds_read_b128 v[26:29], v133
	v_pk_fma_f32 v[136:137], v[100:101], v[30:31], v[2:3] op_sel_hi:[1,0,1]
	v_pk_fma_f32 v[2:3], v[88:89], v[32:33], v[78:79] op_sel_hi:[1,0,1]
	s_waitcnt lgkmcnt(1)
	v_mov_b32_e32 v124, v25
	v_pk_fma_f32 v[2:3], v[92:93], v[32:33], v[2:3] op_sel:[0,1,0]
	ds_read_b128 v[30:33], v135
	v_pk_fma_f32 v[142:143], v[100:101], v[34:35], v[2:3] op_sel_hi:[1,0,1]
	v_pk_fma_f32 v[2:3], v[88:89], v[36:37], v[74:75] op_sel_hi:[1,0,1]
	v_mov_b32_e32 v134, v21
	v_pk_fma_f32 v[2:3], v[92:93], v[36:37], v[2:3] op_sel:[0,1,0]
	ds_read_b128 v[34:37], v139
	v_pk_fma_f32 v[144:145], v[100:101], v[38:39], v[2:3] op_sel_hi:[1,0,1]
	v_pk_fma_f32 v[2:3], v[88:89], v[40:41], v[70:71] op_sel_hi:[1,0,1]
	s_waitcnt vmcnt(15)
	v_mov_b32_e32 v0, v242
	v_mov_b32_e32 v1, v243
	s_mov_b32 s44, 0xfffd0000
	v_lshl_add_u64 v[206:207], v[208:209], 0, s[44:45]
	global_load_dwordx2 v[242:243], v[206:207], off nt
	v_pk_fma_f32 v[112:113], v[0:1], v[106:107], v[112:113] op_sel_hi:[1,0,1]
	v_pk_fma_f32 v[2:3], v[92:93], v[40:41], v[2:3] op_sel:[0,1,0]
	ds_read_b128 v[38:41], v141
	v_pk_fma_f32 v[148:149], v[100:101], v[42:43], v[2:3] op_sel_hi:[1,0,1]
	v_pk_fma_f32 v[2:3], v[88:89], v[44:45], v[62:63] op_sel_hi:[1,0,1]
	s_add_i32 s21, s3, 0xfffea000
	v_pk_fma_f32 v[2:3], v[92:93], v[44:45], v[2:3] op_sel:[0,1,0]
	ds_read_b128 v[42:45], v147
	v_pk_fma_f32 v[154:155], v[100:101], v[46:47], v[2:3] op_sel_hi:[1,0,1]
	v_pk_fma_f32 v[2:3], v[88:89], v[14:15], v[60:61] op_sel_hi:[1,0,1]
	s_add_i32 s22, s3, 0xfffeb000
	v_pk_fma_f32 v[2:3], v[92:93], v[14:15], v[2:3] op_sel:[0,1,0]
	s_waitcnt lgkmcnt(3)
	v_pk_fma_f32 v[14:15], v[88:89], v[30:31], v[94:95] op_sel_hi:[1,0,1]
	v_pk_fma_f32 v[156:157], v[100:101], v[16:17], v[2:3] op_sel_hi:[1,0,1]
	v_pk_fma_f32 v[2:3], v[88:89], v[18:19], v[86:87] op_sel_hi:[1,0,1]
	v_pk_fma_f32 v[14:15], v[92:93], v[30:31], v[14:15] op_sel:[0,1,0]
	v_pk_fma_f32 v[2:3], v[92:93], v[18:19], v[2:3] op_sel:[0,1,0]
	v_pk_fma_f32 v[18:19], v[100:101], v[32:33], v[14:15] op_sel_hi:[1,0,1]
	v_pk_fma_f32 v[130:131], v[100:101], v[20:21], v[2:3] op_sel_hi:[1,0,1]
	v_pk_fma_f32 v[2:3], v[88:89], v[22:23], v[58:59] op_sel_hi:[1,0,1]
	s_waitcnt lgkmcnt(2)
	v_mov_b32_e32 v14, v37
	v_pk_fma_f32 v[2:3], v[92:93], v[22:23], v[2:3] op_sel:[0,1,0]
	v_pk_fma_f32 v[22:23], v[88:89], v[34:35], v[98:99] op_sel_hi:[1,0,1]
	v_pk_fma_f32 v[126:127], v[100:101], v[24:25], v[2:3] op_sel_hi:[1,0,1]
	v_pk_fma_f32 v[22:23], v[92:93], v[34:35], v[22:23] op_sel:[0,1,0]
	v_pk_fma_f32 v[2:3], v[88:89], v[26:27], v[54:55] op_sel_hi:[1,0,1]
	v_pk_fma_f32 v[22:23], v[100:101], v[36:37], v[22:23] op_sel_hi:[1,0,1]
	ds_read_b128 v[34:37], v48
	s_waitcnt lgkmcnt(2)
	v_pk_fma_f32 v[24:25], v[88:89], v[38:39], v[172:173] op_sel_hi:[1,0,1]
	v_pk_fma_f32 v[2:3], v[92:93], v[26:27], v[2:3] op_sel:[0,1,0]
	v_pk_fma_f32 v[24:25], v[92:93], v[38:39], v[24:25] op_sel:[0,1,0]
	s_waitcnt lgkmcnt(1)
	v_pk_fma_f32 v[26:27], v[88:89], v[42:43], v[174:175] op_sel_hi:[1,0,1]
	v_pk_fma_f32 v[2:3], v[100:101], v[28:29], v[2:3] op_sel_hi:[1,0,1]
	v_pk_fma_f32 v[24:25], v[100:101], v[40:41], v[24:25] op_sel_hi:[1,0,1]
	v_mov_b32_e32 v28, v41
	ds_read_b128 v[38:41], v49
	v_pk_fma_f32 v[26:27], v[92:93], v[42:43], v[26:27] op_sel:[0,1,0]
	s_waitcnt lgkmcnt(1)
	v_pk_fma_f32 v[42:43], v[88:89], v[34:35], v[176:177] op_sel_hi:[1,0,1]
	v_pk_fma_f32 v[30:31], v[100:101], v[44:45], v[26:27] op_sel_hi:[1,0,1]
	v_mov_b32_e32 v32, v45
	v_pk_fma_f32 v[34:35], v[92:93], v[34:35], v[42:43] op_sel:[0,1,0]
	ds_read_b128 v[42:45], v50
	ds_read_b128 v[46:49], v151
	v_mov_b32_e32 v26, v37
	v_pk_fma_f32 v[34:35], v[100:101], v[36:37], v[34:35] op_sel_hi:[1,0,1]
	s_waitcnt lgkmcnt(2)
	v_pk_fma_f32 v[36:37], v[88:89], v[38:39], v[180:181] op_sel_hi:[1,0,1]
	v_mov_b32_e32 v15, s6
	v_pk_fma_f32 v[36:37], v[92:93], v[38:39], v[36:37] op_sel:[0,1,0]
	s_waitcnt lgkmcnt(1)
	v_pk_fma_f32 v[38:39], v[88:89], v[42:43], v[182:183] op_sel_hi:[1,0,1]
	s_waitcnt lgkmcnt(0)
	v_pk_fma_f32 v[50:51], v[88:89], v[46:47], v[184:185] op_sel_hi:[1,0,1]
	v_pk_fma_f32 v[38:39], v[92:93], v[42:43], v[38:39] op_sel:[0,1,0]
	v_pk_fma_f32 v[46:47], v[92:93], v[46:47], v[50:51] op_sel:[0,1,0]
	v_pk_fma_f32 v[42:43], v[100:101], v[44:45], v[38:39] op_sel_hi:[1,0,1]
	v_mov_b32_e32 v38, v49
	v_pk_fma_f32 v[46:47], v[100:101], v[48:49], v[46:47] op_sel_hi:[1,0,1]
	ds_read_b128 v[48:51], v159
	ds_read_b128 v[58:61], v188
	v_mov_b32_e32 v17, s7
	s_add_i32 s6, s3, 0xffff6ff0
	s_add_i32 s7, s3, 0xffff7ff0
	s_waitcnt lgkmcnt(1)
	v_pk_fma_f32 v[54:55], v[88:89], v[48:49], v[186:187] op_sel_hi:[1,0,1]
	s_waitcnt lgkmcnt(0)
; #define LAS __attribute__((address_space(3)))
; __device__ __forceinline__ void phase0(CArgs a, LAS unsigned char* lds, int tid, int lane, int wave, int G, int bx) {
;     ...
;                 for (int q = 0; q < 4; ++q) {
; #pragma unroll
;                     for (int r = 0; r < NB; ++r) { const f32x4 s4 = *(const LAS f32x4*)(S + r * 1024 + k + 4 * q);
;                         acc[r] += wv[4 * q] * s4[0]; acc[r] += wv[4 * q + 1] * s4[1]; acc[r] += wv[4 * q + 2] * s4[2]; acc[r] += wv[4 * q + 3] * s4[3]; } }
	v_pk_fma_f32 v[52:53], v[88:89], v[58:59], v[52:53] op_sel_hi:[1,0,1]
	v_pk_fma_f32 v[48:49], v[92:93], v[48:49], v[54:55] op_sel:[0,1,0]
	v_pk_fma_f32 v[52:53], v[92:93], v[58:59], v[52:53] op_sel:[0,1,0]
	v_mov_b32_e32 v54, v61
	v_pk_fma_f32 v[52:53], v[100:101], v[60:61], v[52:53] op_sel_hi:[1,0,1]
	ds_read_b128 v[58:61], v15
	ds_read_b128 v[114:117], v17
	v_mov_b32_e32 v15, s6
	v_mov_b32_e32 v17, s7
	s_add_i32 s6, s3, 0xffff8ff0
	s_waitcnt lgkmcnt(1)
	v_pk_fma_f32 v[56:57], v[88:89], v[58:59], v[56:57] op_sel_hi:[1,0,1]
	s_waitcnt lgkmcnt(0)
	v_mov_b32_e32 v62, v117
	v_pk_fma_f32 v[56:57], v[92:93], v[58:59], v[56:57] op_sel:[0,1,0]
	v_mov_b32_e32 v58, v61
	v_pk_fma_f32 v[56:57], v[100:101], v[60:61], v[56:57] op_sel_hi:[1,0,1]
	v_pk_fma_f32 v[60:61], v[88:89], v[114:115], v[66:67] op_sel_hi:[1,0,1]
	s_add_i32 s7, s3, 0xffff9ff0
	v_pk_fma_f32 v[60:61], v[92:93], v[114:115], v[60:61] op_sel:[0,1,0]
	v_pk_fma_f32 v[176:177], v[0:1], v[124:125], v[126:127] op_sel_hi:[1,0,1]
	v_pk_fma_f32 v[60:61], v[100:101], v[116:117], v[60:61] op_sel_hi:[1,0,1]
	ds_read_b128 v[114:117], v15
	ds_read_b128 v[118:121], v17
	v_mov_b32_e32 v15, s6
	v_mov_b32_e32 v17, s7
	s_add_i32 s6, s3, 0xffffaff0
	s_waitcnt lgkmcnt(1)
	v_pk_fma_f32 v[64:65], v[88:89], v[114:115], v[64:65] op_sel_hi:[1,0,1]
	s_waitcnt lgkmcnt(0)
	v_pk_fma_f32 v[68:69], v[88:89], v[118:119], v[68:69] op_sel_hi:[1,0,1]
	v_pk_fma_f32 v[64:65], v[92:93], v[114:115], v[64:65] op_sel:[0,1,0]
	v_pk_fma_f32 v[68:69], v[92:93], v[118:119], v[68:69] op_sel:[0,1,0]
	v_pk_fma_f32 v[64:65], v[100:101], v[116:117], v[64:65] op_sel_hi:[1,0,1]
	v_mov_b32_e32 v66, v117
	v_pk_fma_f32 v[68:69], v[100:101], v[120:121], v[68:69] op_sel_hi:[1,0,1]
	v_mov_b32_e32 v70, v121
	ds_read_b128 v[114:117], v15
	ds_read_b128 v[118:121], v17
	s_add_i32 s7, s3, 0xffffbff0
	v_mov_b32_e32 v15, s6
	v_mov_b32_e32 v17, s7
	s_waitcnt lgkmcnt(1)
	v_pk_fma_f32 v[72:73], v[88:89], v[114:115], v[72:73] op_sel_hi:[1,0,1]
	s_waitcnt lgkmcnt(0)
	v_pk_fma_f32 v[76:77], v[88:89], v[118:119], v[76:77] op_sel_hi:[1,0,1]
	v_pk_fma_f32 v[72:73], v[92:93], v[114:115], v[72:73] op_sel:[0,1,0]
	v_pk_fma_f32 v[76:77], v[92:93], v[118:119], v[76:77] op_sel:[0,1,0]
	v_pk_fma_f32 v[72:73], v[100:101], v[116:117], v[72:73] op_sel_hi:[1,0,1]
	v_mov_b32_e32 v74, v117
	v_pk_fma_f32 v[76:77], v[100:101], v[120:121], v[76:77] op_sel_hi:[1,0,1]
	v_mov_b32_e32 v78, v121
	ds_read_b128 v[114:117], v15
	ds_read_b128 v[118:121], v17
	s_add_i32 s6, s3, 0xffffcff0
	s_add_i32 s7, s3, 0xffffdff0
	v_mov_b32_e32 v15, s6
	s_waitcnt lgkmcnt(1)
	v_pk_fma_f32 v[80:81], v[88:89], v[114:115], v[80:81] op_sel_hi:[1,0,1]
	s_waitcnt lgkmcnt(0)
	v_pk_fma_f32 v[84:85], v[88:89], v[118:119], v[84:85] op_sel_hi:[1,0,1]
	v_pk_fma_f32 v[80:81], v[92:93], v[114:115], v[80:81] op_sel:[0,1,0]
	v_pk_fma_f32 v[84:85], v[92:93], v[118:119], v[84:85] op_sel:[0,1,0]
	v_pk_fma_f32 v[80:81], v[100:101], v[116:117], v[80:81] op_sel_hi:[1,0,1]
	v_mov_b32_e32 v82, v117
	v_pk_fma_f32 v[84:85], v[100:101], v[120:121], v[84:85] op_sel_hi:[1,0,1]
	v_mov_b32_e32 v86, v121
	v_mov_b32_e32 v17, s7
	ds_read_b128 v[114:117], v15
	ds_read_b128 v[118:121], v17
	s_add_i32 s6, s3, 0xffffeff0
	s_add_i32 s7, s3, -16
	v_mov_b32_e32 v15, s6
	s_waitcnt lgkmcnt(1)
	v_pk_fma_f32 v[90:91], v[88:89], v[114:115], v[90:91] op_sel_hi:[1,0,1]
	s_waitcnt lgkmcnt(0)
	v_pk_fma_f32 v[96:97], v[88:89], v[118:119], v[96:97] op_sel_hi:[1,0,1]
	v_pk_fma_f32 v[90:91], v[92:93], v[114:115], v[90:91] op_sel:[0,1,0]
	v_pk_fma_f32 v[96:97], v[92:93], v[118:119], v[96:97] op_sel:[0,1,0]
	v_pk_fma_f32 v[90:91], v[100:101], v[116:117], v[90:91] op_sel_hi:[1,0,1]
	v_mov_b32_e32 v94, v117
	v_pk_fma_f32 v[96:97], v[100:101], v[120:121], v[96:97] op_sel_hi:[1,0,1]
	v_mov_b32_e32 v98, v121
	v_mov_b32_e32 v17, s7
	ds_read_b128 v[114:117], v15
	ds_read_b128 v[120:123], v17
	s_mov_b32 s6, 0xfffdc000
	v_mov_b32_e32 v16, v29
	s_add_i32 s7, s3, 0xfffe0000
	s_waitcnt lgkmcnt(1)
	v_pk_fma_f32 v[110:111], v[88:89], v[114:115], v[110:111] op_sel_hi:[1,0,1]
	v_mov_b32_e32 v118, v117
	v_pk_fma_f32 v[110:111], v[92:93], v[114:115], v[110:111] op_sel:[0,1,0]
	v_pk_fma_f32 v[180:181], v[0:1], v[16:17], v[2:3] op_sel_hi:[1,0,1]
	v_pk_fma_f32 v[114:115], v[100:101], v[116:117], v[110:111] op_sel_hi:[1,0,1]
	v_pk_fma_f32 v[110:111], v[0:1], v[132:133], v[128:129] op_sel_hi:[1,0,1]
	v_add_co_u32_e32 v128, vcc, s6, v12
	s_mov_b32 s6, 0xfffe8000
	s_nop 0
	v_addc_co_u32_e32 v129, vcc, -1, v13, vcc
	v_pk_fma_f32 v[116:117], v[0:1], v[108:109], v[104:105] op_sel_hi:[1,0,1]
	v_pk_fma_f32 v[108:109], v[0:1], v[134:135], v[130:131] op_sel_hi:[1,0,1]
	v_add_co_u32_e32 v130, vcc, s6, v12
	s_mov_b32 s6, 0xffff4000
	s_nop 0
	v_addc_co_u32_e32 v131, vcc, -1, v13, vcc
	v_add_co_u32_e32 v124, vcc, s6, v12
	s_add_i32 s6, s3, 0xfffdf000
	s_nop 0
	v_addc_co_u32_e32 v125, vcc, -1, v13, vcc
	s_nop 0
	s_nop 0
	v_mov_b32_e32 v2, s6
	v_mov_b32_e32 v20, v33
	v_mov_b32_e32 v3, s7
	v_pk_fma_f32 v[184:185], v[0:1], v[14:15], v[22:23] op_sel_hi:[1,0,1]
	ds_read_b128 v[14:17], v2
	v_pk_fma_f32 v[182:183], v[0:1], v[20:21], v[18:19] op_sel_hi:[1,0,1]
	v_mov_b32_e32 v27, s8
	v_mov_b32_e32 v29, s9
	ds_read_b128 v[18:21], v3
	v_pk_fma_f32 v[186:187], v[0:1], v[28:29], v[24:25] op_sel_hi:[1,0,1]
	ds_read_b128 v[22:25], v27
	v_mov_b32_e32 v33, s14
	v_mov_b32_e32 v44, v45
	s_waitcnt lgkmcnt(3)
; #define LAS __attribute__((address_space(3)))
; __device__ __forceinline__ void phase0(CArgs a, LAS unsigned char* lds, int tid, int lane, int wave, int G, int bx) {
;     ...
;                 for (int i = 0; i < 16; ++i) wv[i] = __builtin_nontemporal_load((const f32x2*)(wp + (size_t)i * NMOD));
; #pragma unroll
;                 for (int q = 0; q < 4; ++q) {
; #pragma unroll
;                     for (int r = 0; r < NB; ++r) { const f32x4 s4 = *(const LAS f32x4*)(S + r * 1024 + k + 4 * q);
;                         acc[r] += wv[4 * q] * s4[0]; acc[r] += wv[4 * q + 1] * s4[1]; acc[r] += wv[4 * q + 2] * s4[2]; acc[r] += wv[4 * q + 3] * s4[3]; } }
	v_pk_fma_f32 v[88:89], v[88:89], v[120:121], v[102:103] op_sel_hi:[1,0,1]
	v_mov_b32_e32 v45, s17
	v_pk_fma_f32 v[188:189], v[0:1], v[32:33], v[30:31] op_sel_hi:[1,0,1]
	v_pk_fma_f32 v[190:191], v[0:1], v[26:27], v[34:35] op_sel_hi:[1,0,1]
	ds_read_b128 v[30:33], v33
	ds_read_b128 v[26:29], v29
	v_pk_fma_f32 v[36:37], v[100:101], v[40:41], v[36:37] op_sel_hi:[1,0,1]
	v_mov_b32_e32 v40, v41
	v_pk_fma_f32 v[88:89], v[92:93], v[120:121], v[88:89] op_sel:[0,1,0]
	s_add_i32 s23, s3, 0xfffec000
	s_add_i32 s25, s3, 0xfffee000
	s_add_i32 s27, s3, 0xffff0000
	s_add_i32 s28, s3, 0xffff1000
	s_add_i32 s29, s3, 0xffff2000
	s_add_i32 s30, s3, 0xffff3000
	v_mov_b32_e32 v39, s15
	v_mov_b32_e32 v41, s16
	v_pk_fma_f32 v[194:195], v[0:1], v[44:45], v[42:43] op_sel_hi:[1,0,1]
	v_pk_fma_f32 v[48:49], v[100:101], v[50:51], v[48:49] op_sel_hi:[1,0,1]
	v_mov_b32_e32 v50, v51
	v_pk_fma_f32 v[120:121], v[100:101], v[122:123], v[88:89] op_sel_hi:[1,0,1]
	v_mov_b32_e32 v122, v123
	v_mov_b32_e32 v51, s18
	v_mov_b32_e32 v55, s19
	v_mov_b32_e32 v59, s20
	v_mov_b32_e32 v63, s21
	v_pk_fma_f32 v[192:193], v[0:1], v[40:41], v[36:37] op_sel_hi:[1,0,1]
	v_mov_b32_e32 v67, s22
	v_mov_b32_e32 v71, s23
	v_mov_b32_e32 v75, s25
	v_mov_b32_e32 v95, s27
	v_mov_b32_e32 v99, s28
	v_mov_b32_e32 v119, s29
	v_mov_b32_e32 v123, s30
	ds_read_b128 v[34:37], v39
	v_pk_fma_f32 v[106:107], v[0:1], v[140:141], v[136:137] op_sel_hi:[1,0,1]
	v_pk_fma_f32 v[104:105], v[0:1], v[138:139], v[142:143] op_sel_hi:[1,0,1]
	v_pk_fma_f32 v[102:103], v[0:1], v[146:147], v[144:145] op_sel_hi:[1,0,1]
	v_pk_fma_f32 v[100:101], v[0:1], v[152:153], v[148:149] op_sel_hi:[1,0,1]
	v_pk_fma_f32 v[92:93], v[0:1], v[150:151], v[154:155] op_sel_hi:[1,0,1]
	v_pk_fma_f32 v[88:89], v[0:1], v[158:159], v[156:157] op_sel_hi:[1,0,1]
	v_pk_fma_f32 v[196:197], v[0:1], v[38:39], v[46:47] op_sel_hi:[1,0,1]
	v_pk_fma_f32 v[198:199], v[0:1], v[50:51], v[48:49] op_sel_hi:[1,0,1]
	v_pk_fma_f32 v[200:201], v[0:1], v[54:55], v[52:53] op_sel_hi:[1,0,1]
	v_pk_fma_f32 v[202:203], v[0:1], v[58:59], v[56:57] op_sel_hi:[1,0,1]
	v_pk_fma_f32 v[204:205], v[0:1], v[62:63], v[60:61] op_sel_hi:[1,0,1]
	v_pk_fma_f32 v[174:175], v[0:1], v[66:67], v[64:65] op_sel_hi:[1,0,1]
	v_pk_fma_f32 v[172:173], v[0:1], v[70:71], v[68:69] op_sel_hi:[1,0,1]
	v_pk_fma_f32 v[170:171], v[0:1], v[74:75], v[72:73] op_sel_hi:[1,0,1]
	v_pk_fma_f32 v[168:169], v[0:1], v[78:79], v[76:77] op_sel_hi:[1,0,1]
	v_pk_fma_f32 v[158:159], v[0:1], v[82:83], v[80:81] op_sel_hi:[1,0,1]
	v_pk_fma_f32 v[156:157], v[0:1], v[86:87], v[84:85] op_sel_hi:[1,0,1]
	v_pk_fma_f32 v[154:155], v[0:1], v[94:95], v[90:91] op_sel_hi:[1,0,1]
	v_pk_fma_f32 v[152:153], v[0:1], v[98:99], v[96:97] op_sel_hi:[1,0,1]
	v_pk_fma_f32 v[124:125], v[0:1], v[118:119], v[114:115] op_sel_hi:[1,0,1]
	ds_read_b128 v[38:41], v41
	v_pk_fma_f32 v[86:87], v[0:1], v[122:123], v[120:121] op_sel_hi:[1,0,1]
	ds_read_b128 v[0:3], v45
	s_waitcnt lgkmcnt(7)
	v_mov_b32_e32 v74, v17
	s_waitcnt lgkmcnt(6)
	v_mov_b32_e32 v80, v21
	s_waitcnt lgkmcnt(5)
	v_mov_b32_e32 v84, v25
	s_waitcnt lgkmcnt(3)
	v_mov_b32_e32 v132, v29
	s_add_i32 s24, s3, 0xfffed000
	v_mov_b32_e32 v138, v33
	s_waitcnt vmcnt(15)
	v_mov_b32_e32 v126, v244
	v_mov_b32_e32 v127, v245
	s_mov_b32 s44, 0xfffdc000
	v_lshl_add_u64 v[206:207], v[208:209], 0, s[44:45]
	global_load_dwordx2 v[244:245], v[206:207], off nt
	v_pk_fma_f32 v[42:43], v[126:127], v[14:15], v[116:117] op_sel_hi:[1,0,1]
	v_mov_b32_e32 v44, s24
	s_waitcnt vmcnt(15)
	v_mov_b32_e32 v128, v246
	v_mov_b32_e32 v129, v247
	s_mov_b32 s44, 0xfffe8000
	v_lshl_add_u64 v[206:207], v[208:209], 0, s[44:45]
	global_load_dwordx2 v[246:247], v[206:207], off nt
	v_pk_fma_f32 v[14:15], v[128:129], v[14:15], v[42:43] op_sel:[0,1,0]
	v_pk_fma_f32 v[42:43], v[126:127], v[18:19], v[112:113] op_sel_hi:[1,0,1]
	s_waitcnt vmcnt(15)
	v_mov_b32_e32 v130, v248
	v_mov_b32_e32 v131, v249
	s_mov_b32 s44, 0xffff4000
	v_lshl_add_u64 v[206:207], v[208:209], 0, s[44:45]
	global_load_dwordx2 v[248:249], v[206:207], off nt
	v_pk_fma_f32 v[76:77], v[130:131], v[16:17], v[14:15] op_sel_hi:[1,0,1]
	v_pk_fma_f32 v[18:19], v[128:129], v[18:19], v[42:43] op_sel:[0,1,0]
	v_pk_fma_f32 v[42:43], v[126:127], v[22:23], v[110:111] op_sel_hi:[1,0,1]
	ds_read_b128 v[14:17], v51
	v_pk_fma_f32 v[22:23], v[128:129], v[22:23], v[42:43] op_sel:[0,1,0]
	v_pk_fma_f32 v[78:79], v[130:131], v[20:21], v[18:19] op_sel_hi:[1,0,1]
	v_pk_fma_f32 v[82:83], v[130:131], v[24:25], v[22:23] op_sel_hi:[1,0,1]
	v_pk_fma_f32 v[22:23], v[126:127], v[26:27], v[106:107] op_sel_hi:[1,0,1]
	ds_read_b128 v[18:21], v55
	v_pk_fma_f32 v[22:23], v[128:129], v[26:27], v[22:23] op_sel:[0,1,0]
	v_pk_fma_f32 v[26:27], v[126:127], v[30:31], v[104:105] op_sel_hi:[1,0,1]
	v_pk_fma_f32 v[134:135], v[130:131], v[28:29], v[22:23] op_sel_hi:[1,0,1]
	v_pk_fma_f32 v[26:27], v[128:129], v[30:31], v[26:27] op_sel:[0,1,0]
	s_waitcnt lgkmcnt(4)
	v_pk_fma_f32 v[30:31], v[126:127], v[34:35], v[102:103] op_sel_hi:[1,0,1]
	ds_read_b128 v[22:25], v59
	v_pk_fma_f32 v[30:31], v[128:129], v[34:35], v[30:31] op_sel:[0,1,0]
	s_waitcnt lgkmcnt(3)
	v_pk_fma_f32 v[34:35], v[126:127], v[0:1], v[92:93] op_sel_hi:[1,0,1]
	v_pk_fma_f32 v[136:137], v[130:131], v[32:33], v[26:27] op_sel_hi:[1,0,1]
	ds_read_b128 v[26:29], v63
	v_pk_fma_f32 v[140:141], v[130:131], v[36:37], v[30:31] op_sel_hi:[1,0,1]
	v_pk_fma_f32 v[30:31], v[126:127], v[38:39], v[100:101] op_sel_hi:[1,0,1]
	v_pk_fma_f32 v[0:1], v[128:129], v[0:1], v[34:35] op_sel:[0,1,0]
	v_pk_fma_f32 v[30:31], v[128:129], v[38:39], v[30:31] op_sel:[0,1,0]
	v_pk_fma_f32 v[148:149], v[130:131], v[2:3], v[0:1] op_sel_hi:[1,0,1]
	s_waitcnt lgkmcnt(3)
; #define LAS __attribute__((address_space(3)))
; __device__ __forceinline__ void phase0(CArgs a, LAS unsigned char* lds, int tid, int lane, int wave, int G, int bx) {
;     ...
;                 for (int q = 0; q < 4; ++q) {
; #pragma unroll
;                     for (int r = 0; r < NB; ++r) { const f32x4 s4 = *(const LAS f32x4*)(S + r * 1024 + k + 4 * q);
;                         acc[r] += wv[4 * q] * s4[0]; acc[r] += wv[4 * q + 1] * s4[1]; acc[r] += wv[4 * q + 2] * s4[2]; acc[r] += wv[4 * q + 3] * s4[3]; } }
	v_pk_fma_f32 v[0:1], v[126:127], v[14:15], v[88:89] op_sel_hi:[1,0,1]
	v_pk_fma_f32 v[146:147], v[130:131], v[40:41], v[30:31] op_sel_hi:[1,0,1]
	ds_read_b128 v[30:33], v67
	v_pk_fma_f32 v[0:1], v[128:129], v[14:15], v[0:1] op_sel:[0,1,0]
	v_mov_b32_e32 v144, v37
	ds_read_b128 v[34:37], v71
	v_pk_fma_f32 v[0:1], v[130:131], v[16:17], v[0:1] op_sel_hi:[1,0,1]
	v_mov_b32_e32 v14, v17
	s_waitcnt lgkmcnt(4)
	v_pk_fma_f32 v[16:17], v[126:127], v[18:19], v[108:109] op_sel_hi:[1,0,1]
	s_add_i32 s26, s3, 0xfffef000
	v_mov_b32_e32 v142, v41
	v_pk_fma_f32 v[16:17], v[128:129], v[18:19], v[16:17] op_sel:[0,1,0]
	ds_read_b128 v[38:41], v44
	s_waitcnt lgkmcnt(4)
	v_pk_fma_f32 v[18:19], v[126:127], v[22:23], v[176:177] op_sel_hi:[1,0,1]
	v_mov_b32_e32 v46, s26
	v_pk_fma_f32 v[18:19], v[128:129], v[22:23], v[18:19] op_sel:[0,1,0]
	s_waitcnt lgkmcnt(3)
	v_pk_fma_f32 v[22:23], v[126:127], v[26:27], v[180:181] op_sel_hi:[1,0,1]
	ds_read_b128 v[46:49], v46
	ds_read_b128 v[42:45], v75
	ds_read_b128 v[50:53], v95
	v_pk_fma_f32 v[22:23], v[128:129], v[26:27], v[22:23] op_sel:[0,1,0]
	v_mov_b32_e32 v26, v29
	v_pk_fma_f32 v[22:23], v[130:131], v[28:29], v[22:23] op_sel_hi:[1,0,1]
	s_waitcnt lgkmcnt(5)
	v_pk_fma_f32 v[28:29], v[126:127], v[30:31], v[182:183] op_sel_hi:[1,0,1]
	ds_read_b128 v[54:57], v99
	ds_read_b128 v[58:61], v119
	v_pk_fma_f32 v[28:29], v[128:129], v[30:31], v[28:29] op_sel:[0,1,0]
	s_waitcnt lgkmcnt(6)
	v_pk_fma_f32 v[30:31], v[126:127], v[34:35], v[184:185] op_sel_hi:[1,0,1]
	s_add_i32 s31, s3, 0xffff4000
	v_pk_fma_f32 v[30:31], v[128:129], v[34:35], v[30:31] op_sel:[0,1,0]
	s_waitcnt lgkmcnt(5)
	v_pk_fma_f32 v[34:35], v[126:127], v[38:39], v[186:187] op_sel_hi:[1,0,1]
	v_mov_b32_e32 v133, s31
	v_pk_fma_f32 v[34:35], v[128:129], v[38:39], v[34:35] op_sel:[0,1,0]
	v_mov_b32_e32 v38, v41
	v_pk_fma_f32 v[34:35], v[130:131], v[40:41], v[34:35] op_sel_hi:[1,0,1]
	s_waitcnt lgkmcnt(3)
	v_pk_fma_f32 v[40:41], v[126:127], v[42:43], v[188:189] op_sel_hi:[1,0,1]
	ds_read_b128 v[62:65], v123
	ds_read_b128 v[66:69], v133
	v_pk_fma_f32 v[40:41], v[128:129], v[42:43], v[40:41] op_sel:[0,1,0]
	v_pk_fma_f32 v[42:43], v[126:127], v[46:47], v[190:191] op_sel_hi:[1,0,1]
	v_mov_b32_e32 v150, v3
	v_pk_fma_f32 v[42:43], v[128:129], v[46:47], v[42:43] op_sel:[0,1,0]
	s_waitcnt lgkmcnt(4)
	v_pk_fma_f32 v[46:47], v[126:127], v[50:51], v[192:193] op_sel_hi:[1,0,1]
	v_mov_b32_e32 v3, s33
	v_pk_fma_f32 v[46:47], v[128:129], v[50:51], v[46:47] op_sel:[0,1,0]
	v_mov_b32_e32 v50, v53
	v_pk_fma_f32 v[46:47], v[130:131], v[52:53], v[46:47] op_sel_hi:[1,0,1]
	s_waitcnt lgkmcnt(3)
	v_pk_fma_f32 v[52:53], v[126:127], v[54:55], v[194:195] op_sel_hi:[1,0,1]
	v_mov_b32_e32 v15, s34
	v_pk_fma_f32 v[52:53], v[128:129], v[54:55], v[52:53] op_sel:[0,1,0]
	s_waitcnt lgkmcnt(2)
	v_pk_fma_f32 v[54:55], v[126:127], v[58:59], v[196:197] op_sel_hi:[1,0,1]
	s_add_i32 s6, s3, 0xffff7000
	v_pk_fma_f32 v[54:55], v[128:129], v[58:59], v[54:55] op_sel:[0,1,0]
	s_waitcnt lgkmcnt(1)
	v_pk_fma_f32 v[58:59], v[126:127], v[62:63], v[198:199] op_sel_hi:[1,0,1]
	s_add_i32 s7, s3, 0xffff8000
	v_pk_fma_f32 v[58:59], v[128:129], v[62:63], v[58:59] op_sel:[0,1,0]
	s_waitcnt lgkmcnt(0)
	v_pk_fma_f32 v[62:63], v[126:127], v[66:67], v[200:201] op_sel_hi:[1,0,1]
	v_pk_fma_f32 v[58:59], v[130:131], v[64:65], v[58:59] op_sel_hi:[1,0,1]
	v_pk_fma_f32 v[62:63], v[128:129], v[66:67], v[62:63] op_sel:[0,1,0]
	v_mov_b32_e32 v64, v69
	v_pk_fma_f32 v[62:63], v[130:131], v[68:69], v[62:63] op_sel_hi:[1,0,1]
	ds_read_b128 v[66:69], v3
	ds_read_b128 v[70:73], v15
	v_mov_b32_e32 v3, s6
	v_mov_b32_e32 v15, s7
	ds_read_b128 v[90:93], v3
	ds_read_b128 v[94:97], v15
	s_waitcnt lgkmcnt(3)
	v_pk_fma_f32 v[88:89], v[126:127], v[66:67], v[202:203] op_sel_hi:[1,0,1]
	s_add_i32 s6, s3, 0xffff9000
	v_pk_fma_f32 v[66:67], v[128:129], v[66:67], v[88:89] op_sel:[0,1,0]
	s_waitcnt lgkmcnt(2)
	v_pk_fma_f32 v[88:89], v[126:127], v[70:71], v[204:205] op_sel_hi:[1,0,1]
	s_add_i32 s7, s3, 0xffffa000
	v_mov_b32_e32 v3, s6
	v_pk_fma_f32 v[70:71], v[128:129], v[70:71], v[88:89] op_sel:[0,1,0]
	s_waitcnt lgkmcnt(1)
	v_pk_fma_f32 v[88:89], v[126:127], v[90:91], v[174:175] op_sel_hi:[1,0,1]
	v_mov_b32_e32 v15, s7
	ds_read_b128 v[98:101], v3
	ds_read_b128 v[102:105], v15
	v_pk_fma_f32 v[88:89], v[128:129], v[90:91], v[88:89] op_sel:[0,1,0]
	s_add_i32 s6, s3, 0xffffb000
	v_pk_fma_f32 v[90:91], v[130:131], v[92:93], v[88:89] op_sel_hi:[1,0,1]
	s_waitcnt lgkmcnt(2)
	v_pk_fma_f32 v[88:89], v[126:127], v[94:95], v[172:173] op_sel_hi:[1,0,1]
	s_add_i32 s7, s3, 0xffffc000
	v_pk_fma_f32 v[88:89], v[128:129], v[94:95], v[88:89] op_sel:[0,1,0]
	v_mov_b32_e32 v3, s6
	v_pk_fma_f32 v[94:95], v[130:131], v[96:97], v[88:89] op_sel_hi:[1,0,1]
	s_waitcnt lgkmcnt(1)
	v_pk_fma_f32 v[88:89], v[126:127], v[98:99], v[170:171] op_sel_hi:[1,0,1]
	v_mov_b32_e32 v15, s7
	ds_read_b128 v[106:109], v3
	ds_read_b128 v[110:113], v15
	v_pk_fma_f32 v[88:89], v[128:129], v[98:99], v[88:89] op_sel:[0,1,0]
	s_add_i32 s6, s3, 0xffffd000
	v_pk_fma_f32 v[98:99], v[130:131], v[100:101], v[88:89] op_sel_hi:[1,0,1]
	s_waitcnt lgkmcnt(2)
	v_pk_fma_f32 v[88:89], v[126:127], v[102:103], v[168:169] op_sel_hi:[1,0,1]
	s_add_i32 s7, s3, 0xffffe000
	v_pk_fma_f32 v[88:89], v[128:129], v[102:103], v[88:89] op_sel:[0,1,0]
	v_mov_b32_e32 v3, s6
	v_pk_fma_f32 v[102:103], v[130:131], v[104:105], v[88:89] op_sel_hi:[1,0,1]
	s_waitcnt lgkmcnt(1)
	v_pk_fma_f32 v[88:89], v[126:127], v[106:107], v[158:159] op_sel_hi:[1,0,1]
	v_mov_b32_e32 v15, s7
	ds_read_b128 v[114:117], v3
	ds_read_b128 v[118:121], v15
	v_pk_fma_f32 v[88:89], v[128:129], v[106:107], v[88:89] op_sel:[0,1,0]
	s_add_i32 s6, s3, 0xfffff000
	v_pk_fma_f32 v[106:107], v[130:131], v[108:109], v[88:89] op_sel_hi:[1,0,1]
	s_waitcnt lgkmcnt(2)
; #define LAS __attribute__((address_space(3)))
; __device__ __forceinline__ void phase0(CArgs a, LAS unsigned char* lds, int tid, int lane, int wave, int G, int bx) {
;     ...
;                 for (int i = 0; i < 16; ++i) wv[i] = __builtin_nontemporal_load((const f32x2*)(wp + (size_t)i * NMOD));
; #pragma unroll
;                 for (int q = 0; q < 4; ++q) {
; #pragma unroll
;                     for (int r = 0; r < NB; ++r) { const f32x4 s4 = *(const LAS f32x4*)(S + r * 1024 + k + 4 * q);
;                         acc[r] += wv[4 * q] * s4[0]; acc[r] += wv[4 * q + 1] * s4[1]; acc[r] += wv[4 * q + 2] * s4[2]; acc[r] += wv[4 * q + 3] * s4[3]; } }
	v_pk_fma_f32 v[88:89], v[126:127], v[110:111], v[156:157] op_sel_hi:[1,0,1]
	v_mov_b32_e32 v15, s6
	v_pk_fma_f32 v[88:89], v[128:129], v[110:111], v[88:89] op_sel:[0,1,0]
	v_mov_b32_e32 v3, s3
	v_pk_fma_f32 v[110:111], v[130:131], v[112:113], v[88:89] op_sel_hi:[1,0,1]
	s_waitcnt lgkmcnt(1)
	v_pk_fma_f32 v[88:89], v[126:127], v[114:115], v[154:155] op_sel_hi:[1,0,1]
	v_pk_fma_f32 v[16:17], v[130:131], v[20:21], v[16:17] op_sel_hi:[1,0,1]
	v_pk_fma_f32 v[88:89], v[128:129], v[114:115], v[88:89] op_sel:[0,1,0]
	v_pk_fma_f32 v[18:19], v[130:131], v[24:25], v[18:19] op_sel_hi:[1,0,1]
	v_pk_fma_f32 v[114:115], v[130:131], v[116:117], v[88:89] op_sel_hi:[1,0,1]
	s_waitcnt lgkmcnt(0)
	v_pk_fma_f32 v[88:89], v[126:127], v[118:119], v[152:153] op_sel_hi:[1,0,1]
	ds_read_b128 v[152:155], v15
	ds_read_b128 v[156:159], v3
	v_pk_fma_f32 v[88:89], v[128:129], v[118:119], v[88:89] op_sel:[0,1,0]
	v_pk_fma_f32 v[28:29], v[130:131], v[32:33], v[28:29] op_sel_hi:[1,0,1]
	v_pk_fma_f32 v[118:119], v[130:131], v[120:121], v[88:89] op_sel_hi:[1,0,1]
	s_waitcnt lgkmcnt(1)
	v_pk_fma_f32 v[88:89], v[126:127], v[152:153], v[124:125] op_sel_hi:[1,0,1]
	s_waitcnt lgkmcnt(0)
	v_pk_fma_f32 v[86:87], v[126:127], v[156:157], v[86:87] op_sel_hi:[1,0,1]
	v_pk_fma_f32 v[88:89], v[128:129], v[152:153], v[88:89] op_sel:[0,1,0]
	v_pk_fma_f32 v[86:87], v[128:129], v[156:157], v[86:87] op_sel:[0,1,0]
	v_pk_fma_f32 v[30:31], v[130:131], v[36:37], v[30:31] op_sel_hi:[1,0,1]
	v_pk_fma_f32 v[40:41], v[130:131], v[44:45], v[40:41] op_sel_hi:[1,0,1]
	v_pk_fma_f32 v[42:43], v[130:131], v[48:49], v[42:43] op_sel_hi:[1,0,1]
	v_pk_fma_f32 v[52:53], v[130:131], v[56:57], v[52:53] op_sel_hi:[1,0,1]
	v_pk_fma_f32 v[54:55], v[130:131], v[60:61], v[54:55] op_sel_hi:[1,0,1]
	v_pk_fma_f32 v[66:67], v[130:131], v[68:69], v[66:67] op_sel_hi:[1,0,1]
	v_pk_fma_f32 v[70:71], v[130:131], v[72:73], v[70:71] op_sel_hi:[1,0,1]
	v_pk_fma_f32 v[122:123], v[130:131], v[154:155], v[88:89] op_sel_hi:[1,0,1]
	v_pk_fma_f32 v[126:127], v[130:131], v[158:159], v[86:87] op_sel_hi:[1,0,1]
	v_mov_b32_e32 v2, v21
	v_mov_b32_e32 v20, v25
	v_mov_b32_e32 v24, v33
	v_mov_b32_e32 v32, v37
	v_mov_b32_e32 v36, v45
	v_mov_b32_e32 v44, v49
	v_mov_b32_e32 v48, v57
	v_mov_b32_e32 v56, v61
	v_mov_b32_e32 v60, v65
	v_mov_b32_e32 v68, v69
	v_mov_b32_e32 v72, v73
	v_mov_b32_e32 v92, v93
	v_mov_b32_e32 v96, v97
	v_mov_b32_e32 v100, v101
	v_mov_b32_e32 v104, v105
	v_mov_b32_e32 v108, v109
	v_mov_b32_e32 v112, v113
	v_mov_b32_e32 v116, v117
	v_mov_b32_e32 v120, v121
	v_mov_b32_e32 v124, v155
	v_mov_b32_e32 v128, v159
	s_add_i32 s3, s3, 64
	s_mov_b64 s[6:7], 0xc0000
	v_lshl_add_u64 v[12:13], v[12:13], 0, s[6:7]
	s_cmpk_gt_u32 s2, 0x6f
	s_waitcnt vmcnt(15)
	v_mov_b32_e32 v130, v250
	v_mov_b32_e32 v131, v251
	global_load_dwordx2 v[250:251], v[208:209], off nt
	v_pk_fma_f32 v[88:89], v[130:131], v[74:75], v[76:77] op_sel_hi:[1,0,1]
	v_pk_fma_f32 v[86:87], v[130:131], v[80:81], v[78:79] op_sel_hi:[1,0,1]
	v_pk_fma_f32 v[84:85], v[130:131], v[84:85], v[82:83] op_sel_hi:[1,0,1]
	v_pk_fma_f32 v[82:83], v[130:131], v[132:133], v[134:135] op_sel_hi:[1,0,1]
	v_pk_fma_f32 v[80:81], v[130:131], v[138:139], v[136:137] op_sel_hi:[1,0,1]
	v_pk_fma_f32 v[78:79], v[130:131], v[144:145], v[140:141] op_sel_hi:[1,0,1]
	v_pk_fma_f32 v[76:77], v[130:131], v[142:143], v[146:147] op_sel_hi:[1,0,1]
	v_pk_fma_f32 v[74:75], v[130:131], v[150:151], v[148:149] op_sel_hi:[1,0,1]
	v_pk_fma_f32 v[152:153], v[130:131], v[14:15], v[0:1] op_sel_hi:[1,0,1]
	v_pk_fma_f32 v[150:151], v[130:131], v[2:3], v[16:17] op_sel_hi:[1,0,1]
	v_pk_fma_f32 v[148:149], v[130:131], v[20:21], v[18:19] op_sel_hi:[1,0,1]
	v_pk_fma_f32 v[146:147], v[130:131], v[26:27], v[22:23] op_sel_hi:[1,0,1]
	v_pk_fma_f32 v[144:145], v[130:131], v[24:25], v[28:29] op_sel_hi:[1,0,1]
	v_pk_fma_f32 v[142:143], v[130:131], v[32:33], v[30:31] op_sel_hi:[1,0,1]
	v_pk_fma_f32 v[140:141], v[130:131], v[38:39], v[34:35] op_sel_hi:[1,0,1]
	v_pk_fma_f32 v[134:135], v[130:131], v[36:37], v[40:41] op_sel_hi:[1,0,1]
	v_pk_fma_f32 v[2:3], v[130:131], v[44:45], v[42:43] op_sel_hi:[1,0,1]
	v_pk_fma_f32 v[0:1], v[130:131], v[50:51], v[46:47] op_sel_hi:[1,0,1]
	v_pk_fma_f32 v[138:139], v[130:131], v[48:49], v[52:53] op_sel_hi:[1,0,1]
	v_pk_fma_f32 v[136:137], v[130:131], v[56:57], v[54:55] op_sel_hi:[1,0,1]
	v_pk_fma_f32 v[132:133], v[130:131], v[60:61], v[58:59] op_sel_hi:[1,0,1]
	v_pk_fma_f32 v[40:41], v[130:131], v[64:65], v[62:63] op_sel_hi:[1,0,1]
	v_pk_fma_f32 v[38:39], v[130:131], v[68:69], v[66:67] op_sel_hi:[1,0,1]
	v_pk_fma_f32 v[36:37], v[130:131], v[72:73], v[70:71] op_sel_hi:[1,0,1]
	v_pk_fma_f32 v[32:33], v[130:131], v[92:93], v[90:91] op_sel_hi:[1,0,1]
	v_pk_fma_f32 v[30:31], v[130:131], v[96:97], v[94:95] op_sel_hi:[1,0,1]
	v_pk_fma_f32 v[28:29], v[130:131], v[100:101], v[98:99] op_sel_hi:[1,0,1]
	v_pk_fma_f32 v[26:27], v[130:131], v[104:105], v[102:103] op_sel_hi:[1,0,1]
	v_pk_fma_f32 v[24:25], v[130:131], v[108:109], v[106:107] op_sel_hi:[1,0,1]
	v_pk_fma_f32 v[22:23], v[130:131], v[112:113], v[110:111] op_sel_hi:[1,0,1]
	v_pk_fma_f32 v[20:21], v[130:131], v[116:117], v[114:115] op_sel_hi:[1,0,1]
	v_pk_fma_f32 v[18:19], v[130:131], v[120:121], v[118:119] op_sel_hi:[1,0,1]
	v_pk_fma_f32 v[16:17], v[130:131], v[124:125], v[122:123] op_sel_hi:[1,0,1]
	v_pk_fma_f32 v[14:15], v[130:131], v[128:129], v[126:127] op_sel_hi:[1,0,1]
	s_cbranch_scc0 .LBB0_843
; #define LAS __attribute__((address_space(3)))
; __device__ __forceinline__ void phase0(CArgs a, LAS unsigned char* lds, int tid, int lane, int wave, int G, int bx) {
;     ...
;         __syncthreads();
; #pragma unroll
;         for (int r = 0; r < NB; ++r) *(LAS f32x2*)(S + (wave * NB + r) * 128 + lane * 2) = acc[r];
;         __syncthreads();
;         float* MOD = (float*)(ws + WS_MOD);
;         for (int idx = tid; idx < NB * 128; idx += 512) { const int r = idx >> 7, col = idx & 127; float s = a->in[11][l * NMOD + cb * 128 + col];
	s_movk_i32 s14, 0x400
	s_mov_b64 s[6:7], 0
	s_and_b64 vcc, exec, s[4:5]
	s_cbranch_vccz .LBB0_835
	s_barrier
	ds_write2st64_b64 v5, v[88:89], v[86:87] offset1:1
	ds_write2st64_b64 v5, v[84:85], v[82:83] offset0:2 offset1:3
	ds_write2st64_b64 v5, v[80:81], v[78:79] offset0:4 offset1:5
	ds_write2st64_b64 v5, v[76:77], v[74:75] offset0:6 offset1:7
	ds_write2st64_b64 v5, v[152:153], v[150:151] offset0:8 offset1:9
	ds_write2st64_b64 v5, v[148:149], v[146:147] offset0:10 offset1:11
	ds_write2st64_b64 v5, v[144:145], v[142:143] offset0:12 offset1:13
	ds_write2st64_b64 v5, v[140:141], v[134:135] offset0:14 offset1:15
	ds_write2st64_b64 v5, v[2:3], v[0:1] offset0:16 offset1:17
	ds_write2st64_b64 v5, v[138:139], v[136:137] offset0:18 offset1:19
	ds_write2st64_b64 v5, v[132:133], v[40:41] offset0:20 offset1:21
	ds_write2st64_b64 v5, v[38:39], v[36:37] offset0:22 offset1:23
	ds_write2st64_b64 v5, v[32:33], v[30:31] offset0:24 offset1:25
	ds_write2st64_b64 v5, v[28:29], v[26:27] offset0:26 offset1:27
	ds_write2st64_b64 v5, v[24:25], v[22:23] offset0:28 offset1:29
	ds_write2st64_b64 v5, v[20:21], v[18:19] offset0:30 offset1:31
	ds_write2st64_b64 v5, v[16:17], v[14:15] offset0:32 offset1:33
	s_waitcnt lgkmcnt(0)
	s_barrier
	s_and_saveexec_b64 s[4:5], s[40:41]
	v_readlane_b32 s28, v254, 20
	s_mov_b64 s[30:31], 0x800
	v_readlane_b32 s29, v254, 21
	s_cbranch_execz .LBB0_833
	s_load_dwordx2 s[2:3], s[92:93], 0x58
	s_mul_i32 s6, s13, 0x3000
	s_add_i32 s6, s6, s0
	v_or_b32_e32 v0, s6, v165
	v_ashrrev_i32_e32 v1, 31, v0
	s_mul_i32 s13, s13, 34
	s_waitcnt lgkmcnt(0)
	v_lshl_add_u64 v[0:1], v[0:1], 2, s[2:3]
	v_lshl_add_u64 v[2:3], s[0:1], 2, v[6:7]
	s_mov_b64 s[0:1], 0
	v_mov_b32_e32 v10, v164
